# step21: + nt policy on read-once loads (scan R/K/V/Z, norm0 x, phase-0 fp32 weights, outproj residual x/xmid, attention Z), on top of step20
# baseline (speedup 1.0000x reference)
.LBB0_29:
	global_load_dword v64, v[10:11], off nt
	v_lshl_add_u64 v[10:11], v[10:11], 0, s[4:5]
	global_load_dword v65, v[10:11], off nt
	v_lshl_add_u64 v[10:11], v[10:11], 0, s[4:5]
	global_load_dword v66, v[10:11], off nt
	v_lshl_add_u64 v[10:11], v[10:11], 0, s[4:5]
	global_load_dword v67, v[10:11], off nt
	v_lshl_add_u64 v[10:11], v[10:11], 0, s[4:5]
	global_load_dword v68, v[10:11], off nt
	v_lshl_add_u64 v[10:11], v[10:11], 0, s[4:5]
	global_load_dword v69, v[10:11], off nt
	v_lshl_add_u64 v[10:11], v[10:11], 0, s[4:5]
	global_load_dword v70, v[10:11], off nt
	v_lshl_add_u64 v[10:11], v[10:11], 0, s[4:5]
	global_load_dword v71, v[10:11], off nt
	v_lshl_add_u64 v[10:11], v[10:11], 0, s[4:5]
	global_load_dword v72, v[10:11], off nt
	v_lshl_add_u64 v[10:11], v[10:11], 0, s[4:5]
	global_load_dword v73, v[10:11], off nt
	v_lshl_add_u64 v[10:11], v[10:11], 0, s[4:5]
	global_load_dword v74, v[10:11], off nt
	v_lshl_add_u64 v[10:11], v[10:11], 0, s[4:5]
	global_load_dword v75, v[10:11], off nt
	v_lshl_add_u64 v[10:11], v[10:11], 0, s[4:5]
	global_load_dword v76, v[10:11], off nt
	v_lshl_add_u64 v[10:11], v[10:11], 0, s[4:5]
	global_load_dword v77, v[10:11], off nt
	v_lshl_add_u64 v[10:11], v[10:11], 0, s[4:5]
	global_load_dword v78, v[10:11], off nt
	v_lshl_add_u64 v[10:11], v[10:11], 0, s[4:5]
	global_load_dword v79, v[10:11], off nt
	v_lshl_add_u64 v[10:11], v[10:11], 0, s[4:5]
	v_add_u32_e32 v56, s23, v3
	ds_read2st64_b32 v[40:41], v56 offset1:16
	ds_read2st64_b32 v[42:43], v56 offset0:32 offset1:48
	ds_read2st64_b32 v[44:45], v56 offset0:64 offset1:80
	ds_read2st64_b32 v[46:47], v56 offset0:96 offset1:112
	ds_read2st64_b32 v[48:49], v56 offset0:128 offset1:144
	ds_read2st64_b32 v[50:51], v56 offset0:160 offset1:176
	ds_read2st64_b32 v[52:53], v56 offset0:192 offset1:208
	ds_read2st64_b32 v[54:55], v56 offset0:224 offset1:240
	v_add_u32_e32 v57, 0x10000, v56
	v_add_u32_e32 v58, 0x11000, v56
	v_add_u32_e32 v59, 0x12000, v56
	v_add_u32_e32 v60, 0x13000, v56
	v_add_u32_e32 v61, 0x14000, v56
	v_add_u32_e32 v62, 0x15000, v56
	v_add_u32_e32 v63, 0x16000, v56
	v_add_u32_e32 v56, 0x17000, v56
	ds_read_b32 v57, v57
	ds_read_b32 v58, v58
	ds_read_b32 v59, v59
	ds_read_b32 v60, v60
	ds_read_b32 v61, v61
	ds_read_b32 v62, v62
	ds_read_b32 v63, v63
	ds_read_b32 v56, v56
	s_add_i32 s23, s23, 4
	s_waitcnt vmcnt(15) lgkmcnt(14)
	v_fmac_f32_e32 v12, v64, v40
	v_fmac_f32_e32 v13, v64, v41
	v_fmac_f32_e32 v17, v64, v42
	v_fmac_f32_e32 v18, v64, v43
	s_waitcnt lgkmcnt(13)
	v_fmac_f32_e32 v19, v64, v44
	v_fmac_f32_e32 v20, v64, v45
	s_waitcnt lgkmcnt(12)
	v_fmac_f32_e32 v21, v64, v46
	v_fmac_f32_e32 v22, v64, v47
	s_waitcnt lgkmcnt(11)
	v_fmac_f32_e32 v23, v64, v48
	v_fmac_f32_e32 v24, v64, v49
	s_waitcnt lgkmcnt(10)
	v_fmac_f32_e32 v25, v64, v50
	v_fmac_f32_e32 v26, v64, v51
	s_waitcnt lgkmcnt(9)
	v_fmac_f32_e32 v27, v64, v52
	v_fmac_f32_e32 v28, v64, v53
	s_waitcnt lgkmcnt(8)
	v_fmac_f32_e32 v29, v64, v54
	v_fmac_f32_e32 v30, v64, v55
	s_waitcnt lgkmcnt(7)
	v_fmac_f32_e32 v31, v64, v57
	s_waitcnt lgkmcnt(6)
	v_fmac_f32_e32 v32, v64, v58
	s_waitcnt lgkmcnt(5)
	v_fmac_f32_e32 v33, v64, v59
	s_waitcnt lgkmcnt(4)
	v_fmac_f32_e32 v34, v64, v60
	s_waitcnt lgkmcnt(3)
	v_fmac_f32_e32 v35, v64, v61
	s_waitcnt lgkmcnt(2)
	v_fmac_f32_e32 v36, v64, v62
	s_waitcnt lgkmcnt(1)
	v_fmac_f32_e32 v37, v64, v63
	s_waitcnt lgkmcnt(0)
	v_fmac_f32_e32 v38, v64, v56
	v_add_u32_e32 v56, s23, v3
	ds_read2st64_b32 v[40:41], v56 offset1:16
	ds_read2st64_b32 v[42:43], v56 offset0:32 offset1:48
	ds_read2st64_b32 v[44:45], v56 offset0:64 offset1:80
	ds_read2st64_b32 v[46:47], v56 offset0:96 offset1:112
	ds_read2st64_b32 v[48:49], v56 offset0:128 offset1:144
	ds_read2st64_b32 v[50:51], v56 offset0:160 offset1:176
	ds_read2st64_b32 v[52:53], v56 offset0:192 offset1:208
	ds_read2st64_b32 v[54:55], v56 offset0:224 offset1:240
	v_add_u32_e32 v57, 0x10000, v56
	v_add_u32_e32 v58, 0x11000, v56
	v_add_u32_e32 v59, 0x12000, v56
	v_add_u32_e32 v60, 0x13000, v56
	v_add_u32_e32 v61, 0x14000, v56
	v_add_u32_e32 v62, 0x15000, v56
	v_add_u32_e32 v63, 0x16000, v56
	v_add_u32_e32 v56, 0x17000, v56
	ds_read_b32 v57, v57
	ds_read_b32 v58, v58
	ds_read_b32 v59, v59
	ds_read_b32 v60, v60
	ds_read_b32 v61, v61
	ds_read_b32 v62, v62
	ds_read_b32 v63, v63
	ds_read_b32 v56, v56
	s_add_i32 s23, s23, 4
	s_waitcnt vmcnt(14) lgkmcnt(14)
	v_fmac_f32_e32 v12, v65, v40
	v_fmac_f32_e32 v13, v65, v41
	v_fmac_f32_e32 v17, v65, v42
	v_fmac_f32_e32 v18, v65, v43
	s_waitcnt lgkmcnt(13)
	v_fmac_f32_e32 v19, v65, v44
	v_fmac_f32_e32 v20, v65, v45
	s_waitcnt lgkmcnt(12)
	v_fmac_f32_e32 v21, v65, v46
	v_fmac_f32_e32 v22, v65, v47
	s_waitcnt lgkmcnt(11)
	v_fmac_f32_e32 v23, v65, v48
	v_fmac_f32_e32 v24, v65, v49
	s_waitcnt lgkmcnt(10)
	v_fmac_f32_e32 v25, v65, v50
	v_fmac_f32_e32 v26, v65, v51
	s_waitcnt lgkmcnt(9)
	v_fmac_f32_e32 v27, v65, v52
	v_fmac_f32_e32 v28, v65, v53
	s_waitcnt lgkmcnt(8)
	v_fmac_f32_e32 v29, v65, v54
	v_fmac_f32_e32 v30, v65, v55
	s_waitcnt lgkmcnt(7)
	v_fmac_f32_e32 v31, v65, v57
	s_waitcnt lgkmcnt(6)
	v_fmac_f32_e32 v32, v65, v58
	s_waitcnt lgkmcnt(5)
	v_fmac_f32_e32 v33, v65, v59
	s_waitcnt lgkmcnt(4)
	v_fmac_f32_e32 v34, v65, v60
	s_waitcnt lgkmcnt(3)
	v_fmac_f32_e32 v35, v65, v61
	s_waitcnt lgkmcnt(2)
	v_fmac_f32_e32 v36, v65, v62
	s_waitcnt lgkmcnt(1)
	v_fmac_f32_e32 v37, v65, v63
	s_waitcnt lgkmcnt(0)
	v_fmac_f32_e32 v38, v65, v56
	v_add_u32_e32 v56, s23, v3
	ds_read2st64_b32 v[40:41], v56 offset1:16
	ds_read2st64_b32 v[42:43], v56 offset0:32 offset1:48
	ds_read2st64_b32 v[44:45], v56 offset0:64 offset1:80
	ds_read2st64_b32 v[46:47], v56 offset0:96 offset1:112
	ds_read2st64_b32 v[48:49], v56 offset0:128 offset1:144
	ds_read2st64_b32 v[50:51], v56 offset0:160 offset1:176
	ds_read2st64_b32 v[52:53], v56 offset0:192 offset1:208
	ds_read2st64_b32 v[54:55], v56 offset0:224 offset1:240
	v_add_u32_e32 v57, 0x10000, v56
	v_add_u32_e32 v58, 0x11000, v56
	v_add_u32_e32 v59, 0x12000, v56
	v_add_u32_e32 v60, 0x13000, v56
	v_add_u32_e32 v61, 0x14000, v56
	v_add_u32_e32 v62, 0x15000, v56
	v_add_u32_e32 v63, 0x16000, v56
	v_add_u32_e32 v56, 0x17000, v56
	ds_read_b32 v57, v57
	ds_read_b32 v58, v58
	ds_read_b32 v59, v59
	ds_read_b32 v60, v60
	ds_read_b32 v61, v61
	ds_read_b32 v62, v62
	ds_read_b32 v63, v63
	ds_read_b32 v56, v56
	s_add_i32 s23, s23, 4
	s_waitcnt vmcnt(13) lgkmcnt(14)
	v_fmac_f32_e32 v12, v66, v40
	v_fmac_f32_e32 v13, v66, v41
	v_fmac_f32_e32 v17, v66, v42
	v_fmac_f32_e32 v18, v66, v43
	s_waitcnt lgkmcnt(13)
	v_fmac_f32_e32 v19, v66, v44
	v_fmac_f32_e32 v20, v66, v45
	s_waitcnt lgkmcnt(12)
	v_fmac_f32_e32 v21, v66, v46
	v_fmac_f32_e32 v22, v66, v47
	s_waitcnt lgkmcnt(11)
	v_fmac_f32_e32 v23, v66, v48
	v_fmac_f32_e32 v24, v66, v49
	s_waitcnt lgkmcnt(10)
	v_fmac_f32_e32 v25, v66, v50
	v_fmac_f32_e32 v26, v66, v51
	s_waitcnt lgkmcnt(9)
	v_fmac_f32_e32 v27, v66, v52
	v_fmac_f32_e32 v28, v66, v53
	s_waitcnt lgkmcnt(8)
	v_fmac_f32_e32 v29, v66, v54
	v_fmac_f32_e32 v30, v66, v55
	s_waitcnt lgkmcnt(7)
	v_fmac_f32_e32 v31, v66, v57
	s_waitcnt lgkmcnt(6)
	v_fmac_f32_e32 v32, v66, v58
	s_waitcnt lgkmcnt(5)
	v_fmac_f32_e32 v33, v66, v59
	s_waitcnt lgkmcnt(4)
	v_fmac_f32_e32 v34, v66, v60
	s_waitcnt lgkmcnt(3)
	v_fmac_f32_e32 v35, v66, v61
	s_waitcnt lgkmcnt(2)
	v_fmac_f32_e32 v36, v66, v62
	s_waitcnt lgkmcnt(1)
	v_fmac_f32_e32 v37, v66, v63
	s_waitcnt lgkmcnt(0)
	v_fmac_f32_e32 v38, v66, v56
	v_add_u32_e32 v56, s23, v3
	ds_read2st64_b32 v[40:41], v56 offset1:16
	ds_read2st64_b32 v[42:43], v56 offset0:32 offset1:48
	ds_read2st64_b32 v[44:45], v56 offset0:64 offset1:80
	ds_read2st64_b32 v[46:47], v56 offset0:96 offset1:112
	ds_read2st64_b32 v[48:49], v56 offset0:128 offset1:144
	ds_read2st64_b32 v[50:51], v56 offset0:160 offset1:176
	ds_read2st64_b32 v[52:53], v56 offset0:192 offset1:208
	ds_read2st64_b32 v[54:55], v56 offset0:224 offset1:240
	v_add_u32_e32 v57, 0x10000, v56
	v_add_u32_e32 v58, 0x11000, v56
	v_add_u32_e32 v59, 0x12000, v56
	v_add_u32_e32 v60, 0x13000, v56
	v_add_u32_e32 v61, 0x14000, v56
	v_add_u32_e32 v62, 0x15000, v56
	v_add_u32_e32 v63, 0x16000, v56
	v_add_u32_e32 v56, 0x17000, v56
	ds_read_b32 v57, v57
	ds_read_b32 v58, v58
	ds_read_b32 v59, v59
	ds_read_b32 v60, v60
	ds_read_b32 v61, v61
	ds_read_b32 v62, v62
	ds_read_b32 v63, v63
	ds_read_b32 v56, v56
	s_add_i32 s23, s23, 4
	s_waitcnt vmcnt(12) lgkmcnt(14)
	v_fmac_f32_e32 v12, v67, v40
	v_fmac_f32_e32 v13, v67, v41
	v_fmac_f32_e32 v17, v67, v42
	v_fmac_f32_e32 v18, v67, v43
	s_waitcnt lgkmcnt(13)
	v_fmac_f32_e32 v19, v67, v44
	v_fmac_f32_e32 v20, v67, v45
	s_waitcnt lgkmcnt(12)
	v_fmac_f32_e32 v21, v67, v46
	v_fmac_f32_e32 v22, v67, v47
	s_waitcnt lgkmcnt(11)
	v_fmac_f32_e32 v23, v67, v48
	v_fmac_f32_e32 v24, v67, v49
	s_waitcnt lgkmcnt(10)
	v_fmac_f32_e32 v25, v67, v50
	v_fmac_f32_e32 v26, v67, v51
	s_waitcnt lgkmcnt(9)
	v_fmac_f32_e32 v27, v67, v52
	v_fmac_f32_e32 v28, v67, v53
	s_waitcnt lgkmcnt(8)
	v_fmac_f32_e32 v29, v67, v54
	v_fmac_f32_e32 v30, v67, v55
	s_waitcnt lgkmcnt(7)
	v_fmac_f32_e32 v31, v67, v57
	s_waitcnt lgkmcnt(6)
	v_fmac_f32_e32 v32, v67, v58
	s_waitcnt lgkmcnt(5)
	v_fmac_f32_e32 v33, v67, v59
	s_waitcnt lgkmcnt(4)
	v_fmac_f32_e32 v34, v67, v60
	s_waitcnt lgkmcnt(3)
	v_fmac_f32_e32 v35, v67, v61
	s_waitcnt lgkmcnt(2)
	v_fmac_f32_e32 v36, v67, v62
	s_waitcnt lgkmcnt(1)
	v_fmac_f32_e32 v37, v67, v63
	s_waitcnt lgkmcnt(0)
	v_fmac_f32_e32 v38, v67, v56
	v_add_u32_e32 v56, s23, v3
	ds_read2st64_b32 v[40:41], v56 offset1:16
	ds_read2st64_b32 v[42:43], v56 offset0:32 offset1:48
	ds_read2st64_b32 v[44:45], v56 offset0:64 offset1:80
	ds_read2st64_b32 v[46:47], v56 offset0:96 offset1:112
	ds_read2st64_b32 v[48:49], v56 offset0:128 offset1:144
	ds_read2st64_b32 v[50:51], v56 offset0:160 offset1:176
	ds_read2st64_b32 v[52:53], v56 offset0:192 offset1:208
	ds_read2st64_b32 v[54:55], v56 offset0:224 offset1:240
	v_add_u32_e32 v57, 0x10000, v56
	v_add_u32_e32 v58, 0x11000, v56
	v_add_u32_e32 v59, 0x12000, v56
	v_add_u32_e32 v60, 0x13000, v56
	v_add_u32_e32 v61, 0x14000, v56
	v_add_u32_e32 v62, 0x15000, v56
	v_add_u32_e32 v63, 0x16000, v56
	v_add_u32_e32 v56, 0x17000, v56
	ds_read_b32 v57, v57
	ds_read_b32 v58, v58
	ds_read_b32 v59, v59
	ds_read_b32 v60, v60
	ds_read_b32 v61, v61
	ds_read_b32 v62, v62
	ds_read_b32 v63, v63
	ds_read_b32 v56, v56
	s_add_i32 s23, s23, 4
	s_waitcnt vmcnt(11) lgkmcnt(14)
	v_fmac_f32_e32 v12, v68, v40
	v_fmac_f32_e32 v13, v68, v41
	v_fmac_f32_e32 v17, v68, v42
	v_fmac_f32_e32 v18, v68, v43
	s_waitcnt lgkmcnt(13)
	v_fmac_f32_e32 v19, v68, v44
	v_fmac_f32_e32 v20, v68, v45
	s_waitcnt lgkmcnt(12)
	v_fmac_f32_e32 v21, v68, v46
	v_fmac_f32_e32 v22, v68, v47
	s_waitcnt lgkmcnt(11)
	v_fmac_f32_e32 v23, v68, v48
	v_fmac_f32_e32 v24, v68, v49
	s_waitcnt lgkmcnt(10)
	v_fmac_f32_e32 v25, v68, v50
	v_fmac_f32_e32 v26, v68, v51
	s_waitcnt lgkmcnt(9)
	v_fmac_f32_e32 v27, v68, v52
	v_fmac_f32_e32 v28, v68, v53
	s_waitcnt lgkmcnt(8)
	v_fmac_f32_e32 v29, v68, v54
	v_fmac_f32_e32 v30, v68, v55
	s_waitcnt lgkmcnt(7)
	v_fmac_f32_e32 v31, v68, v57
	s_waitcnt lgkmcnt(6)
	v_fmac_f32_e32 v32, v68, v58
	s_waitcnt lgkmcnt(5)
	v_fmac_f32_e32 v33, v68, v59
	s_waitcnt lgkmcnt(4)
	v_fmac_f32_e32 v34, v68, v60
	s_waitcnt lgkmcnt(3)
	v_fmac_f32_e32 v35, v68, v61
	s_waitcnt lgkmcnt(2)
	v_fmac_f32_e32 v36, v68, v62
	s_waitcnt lgkmcnt(1)
	v_fmac_f32_e32 v37, v68, v63
	s_waitcnt lgkmcnt(0)
	v_fmac_f32_e32 v38, v68, v56
	v_add_u32_e32 v56, s23, v3
	ds_read2st64_b32 v[40:41], v56 offset1:16
	ds_read2st64_b32 v[42:43], v56 offset0:32 offset1:48
	ds_read2st64_b32 v[44:45], v56 offset0:64 offset1:80
	ds_read2st64_b32 v[46:47], v56 offset0:96 offset1:112
	ds_read2st64_b32 v[48:49], v56 offset0:128 offset1:144
	ds_read2st64_b32 v[50:51], v56 offset0:160 offset1:176
	ds_read2st64_b32 v[52:53], v56 offset0:192 offset1:208
	ds_read2st64_b32 v[54:55], v56 offset0:224 offset1:240
	v_add_u32_e32 v57, 0x10000, v56
	v_add_u32_e32 v58, 0x11000, v56
	v_add_u32_e32 v59, 0x12000, v56
	v_add_u32_e32 v60, 0x13000, v56
	v_add_u32_e32 v61, 0x14000, v56
	v_add_u32_e32 v62, 0x15000, v56
	v_add_u32_e32 v63, 0x16000, v56
	v_add_u32_e32 v56, 0x17000, v56
	ds_read_b32 v57, v57
	ds_read_b32 v58, v58
	ds_read_b32 v59, v59
	ds_read_b32 v60, v60
	ds_read_b32 v61, v61
	ds_read_b32 v62, v62
	ds_read_b32 v63, v63
	ds_read_b32 v56, v56
	s_add_i32 s23, s23, 4
	s_waitcnt vmcnt(10) lgkmcnt(14)
	v_fmac_f32_e32 v12, v69, v40
	v_fmac_f32_e32 v13, v69, v41
	v_fmac_f32_e32 v17, v69, v42
	v_fmac_f32_e32 v18, v69, v43
	s_waitcnt lgkmcnt(13)
	v_fmac_f32_e32 v19, v69, v44
	v_fmac_f32_e32 v20, v69, v45
	s_waitcnt lgkmcnt(12)
	v_fmac_f32_e32 v21, v69, v46
	v_fmac_f32_e32 v22, v69, v47
	s_waitcnt lgkmcnt(11)
	v_fmac_f32_e32 v23, v69, v48
	v_fmac_f32_e32 v24, v69, v49
	s_waitcnt lgkmcnt(10)
	v_fmac_f32_e32 v25, v69, v50
	v_fmac_f32_e32 v26, v69, v51
	s_waitcnt lgkmcnt(9)
	v_fmac_f32_e32 v27, v69, v52
	v_fmac_f32_e32 v28, v69, v53
	s_waitcnt lgkmcnt(8)
	v_fmac_f32_e32 v29, v69, v54
	v_fmac_f32_e32 v30, v69, v55
	s_waitcnt lgkmcnt(7)
	v_fmac_f32_e32 v31, v69, v57
	s_waitcnt lgkmcnt(6)
	v_fmac_f32_e32 v32, v69, v58
	s_waitcnt lgkmcnt(5)
	v_fmac_f32_e32 v33, v69, v59
	s_waitcnt lgkmcnt(4)
	v_fmac_f32_e32 v34, v69, v60
	s_waitcnt lgkmcnt(3)
	v_fmac_f32_e32 v35, v69, v61
	s_waitcnt lgkmcnt(2)
	v_fmac_f32_e32 v36, v69, v62
	s_waitcnt lgkmcnt(1)
	v_fmac_f32_e32 v37, v69, v63
	s_waitcnt lgkmcnt(0)
	v_fmac_f32_e32 v38, v69, v56
	v_add_u32_e32 v56, s23, v3
	ds_read2st64_b32 v[40:41], v56 offset1:16
	ds_read2st64_b32 v[42:43], v56 offset0:32 offset1:48
	ds_read2st64_b32 v[44:45], v56 offset0:64 offset1:80
	ds_read2st64_b32 v[46:47], v56 offset0:96 offset1:112
	ds_read2st64_b32 v[48:49], v56 offset0:128 offset1:144
	ds_read2st64_b32 v[50:51], v56 offset0:160 offset1:176
	ds_read2st64_b32 v[52:53], v56 offset0:192 offset1:208
	ds_read2st64_b32 v[54:55], v56 offset0:224 offset1:240
	v_add_u32_e32 v57, 0x10000, v56
	v_add_u32_e32 v58, 0x11000, v56
	v_add_u32_e32 v59, 0x12000, v56
	v_add_u32_e32 v60, 0x13000, v56
	v_add_u32_e32 v61, 0x14000, v56
	v_add_u32_e32 v62, 0x15000, v56
	v_add_u32_e32 v63, 0x16000, v56
	v_add_u32_e32 v56, 0x17000, v56
	ds_read_b32 v57, v57
	ds_read_b32 v58, v58
	ds_read_b32 v59, v59
	ds_read_b32 v60, v60
	ds_read_b32 v61, v61
	ds_read_b32 v62, v62
	ds_read_b32 v63, v63
	ds_read_b32 v56, v56
	s_add_i32 s23, s23, 4
	s_waitcnt vmcnt(9) lgkmcnt(14)
	v_fmac_f32_e32 v12, v70, v40
	v_fmac_f32_e32 v13, v70, v41
	v_fmac_f32_e32 v17, v70, v42
	v_fmac_f32_e32 v18, v70, v43
	s_waitcnt lgkmcnt(13)
	v_fmac_f32_e32 v19, v70, v44
	v_fmac_f32_e32 v20, v70, v45
	s_waitcnt lgkmcnt(12)
	v_fmac_f32_e32 v21, v70, v46
	v_fmac_f32_e32 v22, v70, v47
	s_waitcnt lgkmcnt(11)
	v_fmac_f32_e32 v23, v70, v48
	v_fmac_f32_e32 v24, v70, v49
	s_waitcnt lgkmcnt(10)
	v_fmac_f32_e32 v25, v70, v50
	v_fmac_f32_e32 v26, v70, v51
	s_waitcnt lgkmcnt(9)
	v_fmac_f32_e32 v27, v70, v52
	v_fmac_f32_e32 v28, v70, v53
	s_waitcnt lgkmcnt(8)
	v_fmac_f32_e32 v29, v70, v54
	v_fmac_f32_e32 v30, v70, v55
	s_waitcnt lgkmcnt(7)
	v_fmac_f32_e32 v31, v70, v57
	s_waitcnt lgkmcnt(6)
	v_fmac_f32_e32 v32, v70, v58
	s_waitcnt lgkmcnt(5)
	v_fmac_f32_e32 v33, v70, v59
	s_waitcnt lgkmcnt(4)
	v_fmac_f32_e32 v34, v70, v60
	s_waitcnt lgkmcnt(3)
	v_fmac_f32_e32 v35, v70, v61
	s_waitcnt lgkmcnt(2)
	v_fmac_f32_e32 v36, v70, v62
	s_waitcnt lgkmcnt(1)
	v_fmac_f32_e32 v37, v70, v63
	s_waitcnt lgkmcnt(0)
	v_fmac_f32_e32 v38, v70, v56
	v_add_u32_e32 v56, s23, v3
	ds_read2st64_b32 v[40:41], v56 offset1:16
	ds_read2st64_b32 v[42:43], v56 offset0:32 offset1:48
	ds_read2st64_b32 v[44:45], v56 offset0:64 offset1:80
	ds_read2st64_b32 v[46:47], v56 offset0:96 offset1:112
	ds_read2st64_b32 v[48:49], v56 offset0:128 offset1:144
	ds_read2st64_b32 v[50:51], v56 offset0:160 offset1:176
	ds_read2st64_b32 v[52:53], v56 offset0:192 offset1:208
	ds_read2st64_b32 v[54:55], v56 offset0:224 offset1:240
	v_add_u32_e32 v57, 0x10000, v56
	v_add_u32_e32 v58, 0x11000, v56
	v_add_u32_e32 v59, 0x12000, v56
	v_add_u32_e32 v60, 0x13000, v56
	v_add_u32_e32 v61, 0x14000, v56
	v_add_u32_e32 v62, 0x15000, v56
	v_add_u32_e32 v63, 0x16000, v56
	v_add_u32_e32 v56, 0x17000, v56
	ds_read_b32 v57, v57
	ds_read_b32 v58, v58
	ds_read_b32 v59, v59
	ds_read_b32 v60, v60
	ds_read_b32 v61, v61
	ds_read_b32 v62, v62
	ds_read_b32 v63, v63
	ds_read_b32 v56, v56
	s_add_i32 s23, s23, 4
	s_waitcnt vmcnt(8) lgkmcnt(14)
	v_fmac_f32_e32 v12, v71, v40
	v_fmac_f32_e32 v13, v71, v41
	v_fmac_f32_e32 v17, v71, v42
	v_fmac_f32_e32 v18, v71, v43
	s_waitcnt lgkmcnt(13)
	v_fmac_f32_e32 v19, v71, v44
	v_fmac_f32_e32 v20, v71, v45
	s_waitcnt lgkmcnt(12)
	v_fmac_f32_e32 v21, v71, v46
	v_fmac_f32_e32 v22, v71, v47
	s_waitcnt lgkmcnt(11)
	v_fmac_f32_e32 v23, v71, v48
	v_fmac_f32_e32 v24, v71, v49
	s_waitcnt lgkmcnt(10)
	v_fmac_f32_e32 v25, v71, v50
	v_fmac_f32_e32 v26, v71, v51
	s_waitcnt lgkmcnt(9)
	v_fmac_f32_e32 v27, v71, v52
	v_fmac_f32_e32 v28, v71, v53
	s_waitcnt lgkmcnt(8)
	v_fmac_f32_e32 v29, v71, v54
	v_fmac_f32_e32 v30, v71, v55
	s_waitcnt lgkmcnt(7)
	v_fmac_f32_e32 v31, v71, v57
	s_waitcnt lgkmcnt(6)
	v_fmac_f32_e32 v32, v71, v58
	s_waitcnt lgkmcnt(5)
	v_fmac_f32_e32 v33, v71, v59
	s_waitcnt lgkmcnt(4)
	v_fmac_f32_e32 v34, v71, v60
	s_waitcnt lgkmcnt(3)
	v_fmac_f32_e32 v35, v71, v61
	s_waitcnt lgkmcnt(2)
	v_fmac_f32_e32 v36, v71, v62
	s_waitcnt lgkmcnt(1)
	v_fmac_f32_e32 v37, v71, v63
	s_waitcnt lgkmcnt(0)
	v_fmac_f32_e32 v38, v71, v56
	v_add_u32_e32 v56, s23, v3
	ds_read2st64_b32 v[40:41], v56 offset1:16
	ds_read2st64_b32 v[42:43], v56 offset0:32 offset1:48
	ds_read2st64_b32 v[44:45], v56 offset0:64 offset1:80
	ds_read2st64_b32 v[46:47], v56 offset0:96 offset1:112
	ds_read2st64_b32 v[48:49], v56 offset0:128 offset1:144
	ds_read2st64_b32 v[50:51], v56 offset0:160 offset1:176
	ds_read2st64_b32 v[52:53], v56 offset0:192 offset1:208
	ds_read2st64_b32 v[54:55], v56 offset0:224 offset1:240
	v_add_u32_e32 v57, 0x10000, v56
	v_add_u32_e32 v58, 0x11000, v56
	v_add_u32_e32 v59, 0x12000, v56
	v_add_u32_e32 v60, 0x13000, v56
	v_add_u32_e32 v61, 0x14000, v56
	v_add_u32_e32 v62, 0x15000, v56
	v_add_u32_e32 v63, 0x16000, v56
	v_add_u32_e32 v56, 0x17000, v56
	ds_read_b32 v57, v57
	ds_read_b32 v58, v58
	ds_read_b32 v59, v59
	ds_read_b32 v60, v60
	ds_read_b32 v61, v61
	ds_read_b32 v62, v62
	ds_read_b32 v63, v63
	ds_read_b32 v56, v56
	s_add_i32 s23, s23, 4
	s_waitcnt vmcnt(7) lgkmcnt(14)
	v_fmac_f32_e32 v12, v72, v40
	v_fmac_f32_e32 v13, v72, v41
	v_fmac_f32_e32 v17, v72, v42
	v_fmac_f32_e32 v18, v72, v43
	s_waitcnt lgkmcnt(13)
	v_fmac_f32_e32 v19, v72, v44
	v_fmac_f32_e32 v20, v72, v45
	s_waitcnt lgkmcnt(12)
	v_fmac_f32_e32 v21, v72, v46
	v_fmac_f32_e32 v22, v72, v47
	s_waitcnt lgkmcnt(11)
	v_fmac_f32_e32 v23, v72, v48
	v_fmac_f32_e32 v24, v72, v49
	s_waitcnt lgkmcnt(10)
	v_fmac_f32_e32 v25, v72, v50
	v_fmac_f32_e32 v26, v72, v51
	s_waitcnt lgkmcnt(9)
	v_fmac_f32_e32 v27, v72, v52
	v_fmac_f32_e32 v28, v72, v53
	s_waitcnt lgkmcnt(8)
	v_fmac_f32_e32 v29, v72, v54
	v_fmac_f32_e32 v30, v72, v55
	s_waitcnt lgkmcnt(7)
	v_fmac_f32_e32 v31, v72, v57
	s_waitcnt lgkmcnt(6)
	v_fmac_f32_e32 v32, v72, v58
	s_waitcnt lgkmcnt(5)
	v_fmac_f32_e32 v33, v72, v59
	s_waitcnt lgkmcnt(4)
	v_fmac_f32_e32 v34, v72, v60
	s_waitcnt lgkmcnt(3)
	v_fmac_f32_e32 v35, v72, v61
	s_waitcnt lgkmcnt(2)
	v_fmac_f32_e32 v36, v72, v62
	s_waitcnt lgkmcnt(1)
	v_fmac_f32_e32 v37, v72, v63
	s_waitcnt lgkmcnt(0)
	v_fmac_f32_e32 v38, v72, v56
	v_add_u32_e32 v56, s23, v3
	ds_read2st64_b32 v[40:41], v56 offset1:16
	ds_read2st64_b32 v[42:43], v56 offset0:32 offset1:48
	ds_read2st64_b32 v[44:45], v56 offset0:64 offset1:80
	ds_read2st64_b32 v[46:47], v56 offset0:96 offset1:112
	ds_read2st64_b32 v[48:49], v56 offset0:128 offset1:144
	ds_read2st64_b32 v[50:51], v56 offset0:160 offset1:176
	ds_read2st64_b32 v[52:53], v56 offset0:192 offset1:208
	ds_read2st64_b32 v[54:55], v56 offset0:224 offset1:240
	v_add_u32_e32 v57, 0x10000, v56
	v_add_u32_e32 v58, 0x11000, v56
	v_add_u32_e32 v59, 0x12000, v56
	v_add_u32_e32 v60, 0x13000, v56
	v_add_u32_e32 v61, 0x14000, v56
	v_add_u32_e32 v62, 0x15000, v56
	v_add_u32_e32 v63, 0x16000, v56
	v_add_u32_e32 v56, 0x17000, v56
	ds_read_b32 v57, v57
	ds_read_b32 v58, v58
	ds_read_b32 v59, v59
	ds_read_b32 v60, v60
	ds_read_b32 v61, v61
	ds_read_b32 v62, v62
	ds_read_b32 v63, v63
	ds_read_b32 v56, v56
	s_add_i32 s23, s23, 4
	s_waitcnt vmcnt(6) lgkmcnt(14)
	v_fmac_f32_e32 v12, v73, v40
	v_fmac_f32_e32 v13, v73, v41
	v_fmac_f32_e32 v17, v73, v42
	v_fmac_f32_e32 v18, v73, v43
	s_waitcnt lgkmcnt(13)
	v_fmac_f32_e32 v19, v73, v44
	v_fmac_f32_e32 v20, v73, v45
	s_waitcnt lgkmcnt(12)
	v_fmac_f32_e32 v21, v73, v46
	v_fmac_f32_e32 v22, v73, v47
	s_waitcnt lgkmcnt(11)
	v_fmac_f32_e32 v23, v73, v48
	v_fmac_f32_e32 v24, v73, v49
	s_waitcnt lgkmcnt(10)
	v_fmac_f32_e32 v25, v73, v50
	v_fmac_f32_e32 v26, v73, v51
	s_waitcnt lgkmcnt(9)
	v_fmac_f32_e32 v27, v73, v52
	v_fmac_f32_e32 v28, v73, v53
	s_waitcnt lgkmcnt(8)
	v_fmac_f32_e32 v29, v73, v54
	v_fmac_f32_e32 v30, v73, v55
	s_waitcnt lgkmcnt(7)
	v_fmac_f32_e32 v31, v73, v57
	s_waitcnt lgkmcnt(6)
	v_fmac_f32_e32 v32, v73, v58
	s_waitcnt lgkmcnt(5)
	v_fmac_f32_e32 v33, v73, v59
	s_waitcnt lgkmcnt(4)
	v_fmac_f32_e32 v34, v73, v60
	s_waitcnt lgkmcnt(3)
	v_fmac_f32_e32 v35, v73, v61
	s_waitcnt lgkmcnt(2)
	v_fmac_f32_e32 v36, v73, v62
	s_waitcnt lgkmcnt(1)
	v_fmac_f32_e32 v37, v73, v63
	s_waitcnt lgkmcnt(0)
	v_fmac_f32_e32 v38, v73, v56
	v_add_u32_e32 v56, s23, v3
	ds_read2st64_b32 v[40:41], v56 offset1:16
	ds_read2st64_b32 v[42:43], v56 offset0:32 offset1:48
	ds_read2st64_b32 v[44:45], v56 offset0:64 offset1:80
	ds_read2st64_b32 v[46:47], v56 offset0:96 offset1:112
	ds_read2st64_b32 v[48:49], v56 offset0:128 offset1:144
	ds_read2st64_b32 v[50:51], v56 offset0:160 offset1:176
	ds_read2st64_b32 v[52:53], v56 offset0:192 offset1:208
	ds_read2st64_b32 v[54:55], v56 offset0:224 offset1:240
	v_add_u32_e32 v57, 0x10000, v56
	v_add_u32_e32 v58, 0x11000, v56
	v_add_u32_e32 v59, 0x12000, v56
	v_add_u32_e32 v60, 0x13000, v56
	v_add_u32_e32 v61, 0x14000, v56
	v_add_u32_e32 v62, 0x15000, v56
	v_add_u32_e32 v63, 0x16000, v56
	v_add_u32_e32 v56, 0x17000, v56
	ds_read_b32 v57, v57
	ds_read_b32 v58, v58
	ds_read_b32 v59, v59
	ds_read_b32 v60, v60
	ds_read_b32 v61, v61
	ds_read_b32 v62, v62
	ds_read_b32 v63, v63
	ds_read_b32 v56, v56
	s_add_i32 s23, s23, 4
	s_waitcnt vmcnt(5) lgkmcnt(14)
	v_fmac_f32_e32 v12, v74, v40
	v_fmac_f32_e32 v13, v74, v41
	v_fmac_f32_e32 v17, v74, v42
	v_fmac_f32_e32 v18, v74, v43
	s_waitcnt lgkmcnt(13)
	v_fmac_f32_e32 v19, v74, v44
	v_fmac_f32_e32 v20, v74, v45
	s_waitcnt lgkmcnt(12)
	v_fmac_f32_e32 v21, v74, v46
	v_fmac_f32_e32 v22, v74, v47
	s_waitcnt lgkmcnt(11)
	v_fmac_f32_e32 v23, v74, v48
	v_fmac_f32_e32 v24, v74, v49
	s_waitcnt lgkmcnt(10)
	v_fmac_f32_e32 v25, v74, v50
	v_fmac_f32_e32 v26, v74, v51
	s_waitcnt lgkmcnt(9)
	v_fmac_f32_e32 v27, v74, v52
	v_fmac_f32_e32 v28, v74, v53
	s_waitcnt lgkmcnt(8)
	v_fmac_f32_e32 v29, v74, v54
	v_fmac_f32_e32 v30, v74, v55
	s_waitcnt lgkmcnt(7)
	v_fmac_f32_e32 v31, v74, v57
	s_waitcnt lgkmcnt(6)
	v_fmac_f32_e32 v32, v74, v58
	s_waitcnt lgkmcnt(5)
	v_fmac_f32_e32 v33, v74, v59
	s_waitcnt lgkmcnt(4)
	v_fmac_f32_e32 v34, v74, v60
	s_waitcnt lgkmcnt(3)
	v_fmac_f32_e32 v35, v74, v61
	s_waitcnt lgkmcnt(2)
	v_fmac_f32_e32 v36, v74, v62
	s_waitcnt lgkmcnt(1)
	v_fmac_f32_e32 v37, v74, v63
	s_waitcnt lgkmcnt(0)
	v_fmac_f32_e32 v38, v74, v56
	v_add_u32_e32 v56, s23, v3
	ds_read2st64_b32 v[40:41], v56 offset1:16
	ds_read2st64_b32 v[42:43], v56 offset0:32 offset1:48
	ds_read2st64_b32 v[44:45], v56 offset0:64 offset1:80
	ds_read2st64_b32 v[46:47], v56 offset0:96 offset1:112
	ds_read2st64_b32 v[48:49], v56 offset0:128 offset1:144
	ds_read2st64_b32 v[50:51], v56 offset0:160 offset1:176
	ds_read2st64_b32 v[52:53], v56 offset0:192 offset1:208
	ds_read2st64_b32 v[54:55], v56 offset0:224 offset1:240
	v_add_u32_e32 v57, 0x10000, v56
	v_add_u32_e32 v58, 0x11000, v56
	v_add_u32_e32 v59, 0x12000, v56
	v_add_u32_e32 v60, 0x13000, v56
	v_add_u32_e32 v61, 0x14000, v56
	v_add_u32_e32 v62, 0x15000, v56
	v_add_u32_e32 v63, 0x16000, v56
	v_add_u32_e32 v56, 0x17000, v56
	ds_read_b32 v57, v57
	ds_read_b32 v58, v58
	ds_read_b32 v59, v59
	ds_read_b32 v60, v60
	ds_read_b32 v61, v61
	ds_read_b32 v62, v62
	ds_read_b32 v63, v63
	ds_read_b32 v56, v56
	s_add_i32 s23, s23, 4
	s_waitcnt vmcnt(4) lgkmcnt(14)
	v_fmac_f32_e32 v12, v75, v40
	v_fmac_f32_e32 v13, v75, v41
	v_fmac_f32_e32 v17, v75, v42
	v_fmac_f32_e32 v18, v75, v43
	s_waitcnt lgkmcnt(13)
	v_fmac_f32_e32 v19, v75, v44
	v_fmac_f32_e32 v20, v75, v45
	s_waitcnt lgkmcnt(12)
	v_fmac_f32_e32 v21, v75, v46
	v_fmac_f32_e32 v22, v75, v47
	s_waitcnt lgkmcnt(11)
	v_fmac_f32_e32 v23, v75, v48
	v_fmac_f32_e32 v24, v75, v49
	s_waitcnt lgkmcnt(10)
	v_fmac_f32_e32 v25, v75, v50
	v_fmac_f32_e32 v26, v75, v51
	s_waitcnt lgkmcnt(9)
	v_fmac_f32_e32 v27, v75, v52
	v_fmac_f32_e32 v28, v75, v53
	s_waitcnt lgkmcnt(8)
	v_fmac_f32_e32 v29, v75, v54
	v_fmac_f32_e32 v30, v75, v55
	s_waitcnt lgkmcnt(7)
	v_fmac_f32_e32 v31, v75, v57
	s_waitcnt lgkmcnt(6)
	v_fmac_f32_e32 v32, v75, v58
	s_waitcnt lgkmcnt(5)
	v_fmac_f32_e32 v33, v75, v59
	s_waitcnt lgkmcnt(4)
	v_fmac_f32_e32 v34, v75, v60
	s_waitcnt lgkmcnt(3)
	v_fmac_f32_e32 v35, v75, v61
	s_waitcnt lgkmcnt(2)
	v_fmac_f32_e32 v36, v75, v62
	s_waitcnt lgkmcnt(1)
	v_fmac_f32_e32 v37, v75, v63
	s_waitcnt lgkmcnt(0)
	v_fmac_f32_e32 v38, v75, v56
	v_add_u32_e32 v56, s23, v3
	ds_read2st64_b32 v[40:41], v56 offset1:16
	ds_read2st64_b32 v[42:43], v56 offset0:32 offset1:48
	ds_read2st64_b32 v[44:45], v56 offset0:64 offset1:80
	ds_read2st64_b32 v[46:47], v56 offset0:96 offset1:112
	ds_read2st64_b32 v[48:49], v56 offset0:128 offset1:144
	ds_read2st64_b32 v[50:51], v56 offset0:160 offset1:176
	ds_read2st64_b32 v[52:53], v56 offset0:192 offset1:208
	ds_read2st64_b32 v[54:55], v56 offset0:224 offset1:240
	v_add_u32_e32 v57, 0x10000, v56
	v_add_u32_e32 v58, 0x11000, v56
	v_add_u32_e32 v59, 0x12000, v56
	v_add_u32_e32 v60, 0x13000, v56
	v_add_u32_e32 v61, 0x14000, v56
	v_add_u32_e32 v62, 0x15000, v56
	v_add_u32_e32 v63, 0x16000, v56
	v_add_u32_e32 v56, 0x17000, v56
	ds_read_b32 v57, v57
	ds_read_b32 v58, v58
	ds_read_b32 v59, v59
	ds_read_b32 v60, v60
	ds_read_b32 v61, v61
	ds_read_b32 v62, v62
	ds_read_b32 v63, v63
	ds_read_b32 v56, v56
	s_add_i32 s23, s23, 4
	s_waitcnt vmcnt(3) lgkmcnt(14)
	v_fmac_f32_e32 v12, v76, v40
	v_fmac_f32_e32 v13, v76, v41
	v_fmac_f32_e32 v17, v76, v42
	v_fmac_f32_e32 v18, v76, v43
	s_waitcnt lgkmcnt(13)
	v_fmac_f32_e32 v19, v76, v44
	v_fmac_f32_e32 v20, v76, v45
	s_waitcnt lgkmcnt(12)
	v_fmac_f32_e32 v21, v76, v46
	v_fmac_f32_e32 v22, v76, v47
	s_waitcnt lgkmcnt(11)
	v_fmac_f32_e32 v23, v76, v48
	v_fmac_f32_e32 v24, v76, v49
	s_waitcnt lgkmcnt(10)
	v_fmac_f32_e32 v25, v76, v50
	v_fmac_f32_e32 v26, v76, v51
	s_waitcnt lgkmcnt(9)
	v_fmac_f32_e32 v27, v76, v52
	v_fmac_f32_e32 v28, v76, v53
	s_waitcnt lgkmcnt(8)
	v_fmac_f32_e32 v29, v76, v54
	v_fmac_f32_e32 v30, v76, v55
	s_waitcnt lgkmcnt(7)
	v_fmac_f32_e32 v31, v76, v57
	s_waitcnt lgkmcnt(6)
	v_fmac_f32_e32 v32, v76, v58
	s_waitcnt lgkmcnt(5)
	v_fmac_f32_e32 v33, v76, v59
	s_waitcnt lgkmcnt(4)
	v_fmac_f32_e32 v34, v76, v60
	s_waitcnt lgkmcnt(3)
	v_fmac_f32_e32 v35, v76, v61
	s_waitcnt lgkmcnt(2)
	v_fmac_f32_e32 v36, v76, v62
	s_waitcnt lgkmcnt(1)
	v_fmac_f32_e32 v37, v76, v63
	s_waitcnt lgkmcnt(0)
	v_fmac_f32_e32 v38, v76, v56
	v_add_u32_e32 v56, s23, v3
	ds_read2st64_b32 v[40:41], v56 offset1:16
	ds_read2st64_b32 v[42:43], v56 offset0:32 offset1:48
	ds_read2st64_b32 v[44:45], v56 offset0:64 offset1:80
	ds_read2st64_b32 v[46:47], v56 offset0:96 offset1:112
	ds_read2st64_b32 v[48:49], v56 offset0:128 offset1:144
	ds_read2st64_b32 v[50:51], v56 offset0:160 offset1:176
	ds_read2st64_b32 v[52:53], v56 offset0:192 offset1:208
	ds_read2st64_b32 v[54:55], v56 offset0:224 offset1:240
	v_add_u32_e32 v57, 0x10000, v56
	v_add_u32_e32 v58, 0x11000, v56
	v_add_u32_e32 v59, 0x12000, v56
	v_add_u32_e32 v60, 0x13000, v56
	v_add_u32_e32 v61, 0x14000, v56
	v_add_u32_e32 v62, 0x15000, v56
	v_add_u32_e32 v63, 0x16000, v56
	v_add_u32_e32 v56, 0x17000, v56
	ds_read_b32 v57, v57
	ds_read_b32 v58, v58
	ds_read_b32 v59, v59
	ds_read_b32 v60, v60
	ds_read_b32 v61, v61
	ds_read_b32 v62, v62
	ds_read_b32 v63, v63
	ds_read_b32 v56, v56
	s_add_i32 s23, s23, 4
	s_waitcnt vmcnt(2) lgkmcnt(14)
	v_fmac_f32_e32 v12, v77, v40
	v_fmac_f32_e32 v13, v77, v41
	v_fmac_f32_e32 v17, v77, v42
	v_fmac_f32_e32 v18, v77, v43
	s_waitcnt lgkmcnt(13)
	v_fmac_f32_e32 v19, v77, v44
	v_fmac_f32_e32 v20, v77, v45
	s_waitcnt lgkmcnt(12)
	v_fmac_f32_e32 v21, v77, v46
	v_fmac_f32_e32 v22, v77, v47
	s_waitcnt lgkmcnt(11)
	v_fmac_f32_e32 v23, v77, v48
	v_fmac_f32_e32 v24, v77, v49
	s_waitcnt lgkmcnt(10)
	v_fmac_f32_e32 v25, v77, v50
	v_fmac_f32_e32 v26, v77, v51
	s_waitcnt lgkmcnt(9)
	v_fmac_f32_e32 v27, v77, v52
	v_fmac_f32_e32 v28, v77, v53
	s_waitcnt lgkmcnt(8)
	v_fmac_f32_e32 v29, v77, v54
	v_fmac_f32_e32 v30, v77, v55
	s_waitcnt lgkmcnt(7)
	v_fmac_f32_e32 v31, v77, v57
	s_waitcnt lgkmcnt(6)
	v_fmac_f32_e32 v32, v77, v58
	s_waitcnt lgkmcnt(5)
	v_fmac_f32_e32 v33, v77, v59
	s_waitcnt lgkmcnt(4)
	v_fmac_f32_e32 v34, v77, v60
	s_waitcnt lgkmcnt(3)
	v_fmac_f32_e32 v35, v77, v61
	s_waitcnt lgkmcnt(2)
	v_fmac_f32_e32 v36, v77, v62
	s_waitcnt lgkmcnt(1)
	v_fmac_f32_e32 v37, v77, v63
	s_waitcnt lgkmcnt(0)
	v_fmac_f32_e32 v38, v77, v56
	v_add_u32_e32 v56, s23, v3
	ds_read2st64_b32 v[40:41], v56 offset1:16
	ds_read2st64_b32 v[42:43], v56 offset0:32 offset1:48
	ds_read2st64_b32 v[44:45], v56 offset0:64 offset1:80
	ds_read2st64_b32 v[46:47], v56 offset0:96 offset1:112
	ds_read2st64_b32 v[48:49], v56 offset0:128 offset1:144
	ds_read2st64_b32 v[50:51], v56 offset0:160 offset1:176
	ds_read2st64_b32 v[52:53], v56 offset0:192 offset1:208
	ds_read2st64_b32 v[54:55], v56 offset0:224 offset1:240
	v_add_u32_e32 v57, 0x10000, v56
	v_add_u32_e32 v58, 0x11000, v56
	v_add_u32_e32 v59, 0x12000, v56
	v_add_u32_e32 v60, 0x13000, v56
	v_add_u32_e32 v61, 0x14000, v56
	v_add_u32_e32 v62, 0x15000, v56
	v_add_u32_e32 v63, 0x16000, v56
	v_add_u32_e32 v56, 0x17000, v56
	ds_read_b32 v57, v57
	ds_read_b32 v58, v58
	ds_read_b32 v59, v59
	ds_read_b32 v60, v60
	ds_read_b32 v61, v61
	ds_read_b32 v62, v62
	ds_read_b32 v63, v63
	ds_read_b32 v56, v56
	s_add_i32 s23, s23, 4
	s_waitcnt vmcnt(1) lgkmcnt(14)
	v_fmac_f32_e32 v12, v78, v40
	v_fmac_f32_e32 v13, v78, v41
	v_fmac_f32_e32 v17, v78, v42
	v_fmac_f32_e32 v18, v78, v43
	s_waitcnt lgkmcnt(13)
	v_fmac_f32_e32 v19, v78, v44
	v_fmac_f32_e32 v20, v78, v45
	s_waitcnt lgkmcnt(12)
	v_fmac_f32_e32 v21, v78, v46
	v_fmac_f32_e32 v22, v78, v47
	s_waitcnt lgkmcnt(11)
	v_fmac_f32_e32 v23, v78, v48
	v_fmac_f32_e32 v24, v78, v49
	s_waitcnt lgkmcnt(10)
	v_fmac_f32_e32 v25, v78, v50
	v_fmac_f32_e32 v26, v78, v51
	s_waitcnt lgkmcnt(9)
	v_fmac_f32_e32 v27, v78, v52
	v_fmac_f32_e32 v28, v78, v53
	s_waitcnt lgkmcnt(8)
	v_fmac_f32_e32 v29, v78, v54
	v_fmac_f32_e32 v30, v78, v55
	s_waitcnt lgkmcnt(7)
	v_fmac_f32_e32 v31, v78, v57
	s_waitcnt lgkmcnt(6)
	v_fmac_f32_e32 v32, v78, v58
	s_waitcnt lgkmcnt(5)
	v_fmac_f32_e32 v33, v78, v59
	s_waitcnt lgkmcnt(4)
	v_fmac_f32_e32 v34, v78, v60
	s_waitcnt lgkmcnt(3)
	v_fmac_f32_e32 v35, v78, v61
	s_waitcnt lgkmcnt(2)
	v_fmac_f32_e32 v36, v78, v62
	s_waitcnt lgkmcnt(1)
	v_fmac_f32_e32 v37, v78, v63
	s_waitcnt lgkmcnt(0)
	v_fmac_f32_e32 v38, v78, v56
	v_add_u32_e32 v56, s23, v3
	ds_read2st64_b32 v[40:41], v56 offset1:16
	ds_read2st64_b32 v[42:43], v56 offset0:32 offset1:48
	ds_read2st64_b32 v[44:45], v56 offset0:64 offset1:80
	ds_read2st64_b32 v[46:47], v56 offset0:96 offset1:112
	ds_read2st64_b32 v[48:49], v56 offset0:128 offset1:144
	ds_read2st64_b32 v[50:51], v56 offset0:160 offset1:176
	ds_read2st64_b32 v[52:53], v56 offset0:192 offset1:208
	ds_read2st64_b32 v[54:55], v56 offset0:224 offset1:240
	v_add_u32_e32 v57, 0x10000, v56
	v_add_u32_e32 v58, 0x11000, v56
	v_add_u32_e32 v59, 0x12000, v56
	v_add_u32_e32 v60, 0x13000, v56
	v_add_u32_e32 v61, 0x14000, v56
	v_add_u32_e32 v62, 0x15000, v56
	v_add_u32_e32 v63, 0x16000, v56
	v_add_u32_e32 v56, 0x17000, v56
	ds_read_b32 v57, v57
	ds_read_b32 v58, v58
	ds_read_b32 v59, v59
	ds_read_b32 v60, v60
	ds_read_b32 v61, v61
	ds_read_b32 v62, v62
	ds_read_b32 v63, v63
	ds_read_b32 v56, v56
	s_add_i32 s23, s23, 4
	s_waitcnt vmcnt(0) lgkmcnt(14)
	v_fmac_f32_e32 v12, v79, v40
	v_fmac_f32_e32 v13, v79, v41
	v_fmac_f32_e32 v17, v79, v42
	v_fmac_f32_e32 v18, v79, v43
	s_waitcnt lgkmcnt(13)
	v_fmac_f32_e32 v19, v79, v44
	v_fmac_f32_e32 v20, v79, v45
	s_waitcnt lgkmcnt(12)
	v_fmac_f32_e32 v21, v79, v46
	v_fmac_f32_e32 v22, v79, v47
	s_waitcnt lgkmcnt(11)
	v_fmac_f32_e32 v23, v79, v48
	v_fmac_f32_e32 v24, v79, v49
	s_waitcnt lgkmcnt(10)
	v_fmac_f32_e32 v25, v79, v50
	v_fmac_f32_e32 v26, v79, v51
	s_waitcnt lgkmcnt(9)
	v_fmac_f32_e32 v27, v79, v52
	v_fmac_f32_e32 v28, v79, v53
	s_waitcnt lgkmcnt(8)
	v_fmac_f32_e32 v29, v79, v54
	v_fmac_f32_e32 v30, v79, v55
	s_waitcnt lgkmcnt(7)
	v_fmac_f32_e32 v31, v79, v57
	s_waitcnt lgkmcnt(6)
	v_fmac_f32_e32 v32, v79, v58
	s_waitcnt lgkmcnt(5)
	v_fmac_f32_e32 v33, v79, v59
	s_waitcnt lgkmcnt(4)
	v_fmac_f32_e32 v34, v79, v60
	s_waitcnt lgkmcnt(3)
	v_fmac_f32_e32 v35, v79, v61
	s_waitcnt lgkmcnt(2)
	v_fmac_f32_e32 v36, v79, v62
	s_waitcnt lgkmcnt(1)
	v_fmac_f32_e32 v37, v79, v63
	s_waitcnt lgkmcnt(0)
	v_fmac_f32_e32 v38, v79, v56
	s_cmpk_eq_i32 s23, 0x200
	s_cbranch_scc0 .LBB0_29
	s_and_b64 s[34:35], s[34:35], exec
	s_cselect_b32 s23, s57, s25
	s_cselect_b32 s34, s56, s24
	ds_write2st64_b32 v16, v12, v13 offset1:1
	ds_write2st64_b32 v16, v17, v18 offset0:2 offset1:3
	ds_write2st64_b32 v16, v19, v20 offset0:4 offset1:5
	ds_write2st64_b32 v16, v21, v22 offset0:6 offset1:7
	ds_write2st64_b32 v16, v23, v24 offset0:8 offset1:9
	ds_write2st64_b32 v16, v25, v26 offset0:10 offset1:11
	ds_write2st64_b32 v16, v27, v28 offset0:12 offset1:13
	ds_write2st64_b32 v16, v29, v30 offset0:14 offset1:15
	ds_write2st64_b32 v16, v31, v32 offset0:16 offset1:17
	ds_write2st64_b32 v16, v33, v34 offset0:18 offset1:19
	ds_write2st64_b32 v16, v35, v36 offset0:20 offset1:21
	ds_write2st64_b32 v16, v37, v38 offset0:22 offset1:23
	v_or_b32_e32 v12, s22, v1
	v_mov_b32_e32 v10, s34
	v_mov_b32_e32 v11, s23
	v_ashrrev_i32_e32 v13, 31, v12
	v_lshl_add_u64 v[10:11], v[12:13], 2, v[10:11]
	v_mad_u64_u32 v[12:13], s[22:23], s92, 24, v[4:5]
	v_mov_b64_e32 v[18:19], s[20:21]
	v_mad_i64_i32 v[12:13], s[20:21], v12, s3, v[18:19]
	v_lshl_add_u64 v[12:13], v[8:9], 0, v[12:13]
	s_mov_b64 s[20:21], 0
	v_mov_b32_e32 v17, v15
	v_mov_b32_e32 v18, v5
	s_waitcnt lgkmcnt(0)
	s_barrier

.LBB0_46:
	s_lshr_b32 s92, s54, 8
	v_cvt_f32_u32_e32 v2, s92
	s_sub_i32 vcc_lo, 0, s92
	s_abs_i32 s96, s97
	s_ashr_i32 s93, s97, 31
	v_rcp_iflag_f32_e32 v2, v2
	v_mov_b32_e32 v15, v11
	v_mov_b32_e32 v17, v11
	v_mul_f32_e32 v2, 0x4f7ffffe, v2
	v_cvt_u32_f32_e32 v2, v2
	s_nop 0
	v_readfirstlane_b32 vcc_hi, v2
	s_mul_i32 vcc_lo, vcc_lo, vcc_hi
	s_mul_hi_u32 vcc_lo, vcc_hi, vcc_lo
	s_add_i32 vcc_hi, vcc_hi, vcc_lo
	s_mul_hi_u32 vcc_lo, s96, vcc_hi
	s_mul_i32 vcc_hi, vcc_lo, s92
	s_sub_i32 s96, s96, vcc_hi
	s_add_i32 vcc_hi, vcc_lo, 1
	s_sub_i32 s6, s96, s92
	s_cmp_ge_u32 s96, s92
	s_cselect_b32 s7, vcc_hi, vcc_lo
	s_cselect_b32 s6, s6, s96
	s_add_i32 s96, s7, 1
	s_cmp_ge_u32 s6, s92
	s_cselect_b32 s6, s96, s7
	s_xor_b32 s6, s6, s93
	s_sub_i32 s6, s6, s93
	s_lshl_b32 s96, s6, 6
	s_mul_i32 s6, s6, s92
	s_sub_i32 s6, s97, s6
	s_lshl_b32 s92, s6, 8
	s_ashr_i32 s93, s92, 31
	s_lshl_b64 vcc, s[92:93], 2
	s_add_u32 s88, s88, vcc_lo
	s_addc_u32 s89, s89, vcc_hi
	v_or_b32_e32 v2, s96, v21
	s_ashr_i32 s97, s96, 31
	v_lshl_add_u64 v[6:7], s[88:89], 0, v[14:15]
	v_mad_u64_u32 v[2:3], s[88:89], v2, s54, 0
	s_mul_i32 s6, s97, s54
	v_add_u32_e32 v3, s6, v3
	v_lshl_add_u64 v[2:3], v[2:3], 2, v[6:7]
	global_load_dwordx4 v[64:67], v[2:3], off nt
	v_or_b32_e32 v2, s96, v22
	v_mad_u64_u32 v[2:3], s[88:89], v2, s54, 0
	v_add_u32_e32 v3, s6, v3
	v_lshl_add_u64 v[2:3], v[2:3], 2, v[6:7]
	global_load_dwordx4 v[68:71], v[2:3], off nt
	v_or_b32_e32 v2, s96, v23
	v_mad_u64_u32 v[2:3], s[88:89], v2, s54, 0
	v_add_u32_e32 v3, s6, v3
	v_lshl_add_u64 v[2:3], v[2:3], 2, v[6:7]
	global_load_dwordx4 v[72:75], v[2:3], off nt
	v_or_b32_e32 v2, s96, v24
	v_mad_u64_u32 v[2:3], s[88:89], v2, s54, 0
	v_add_u32_e32 v3, s6, v3
	v_lshl_add_u64 v[2:3], v[2:3], 2, v[6:7]
	global_load_dwordx4 v[76:79], v[2:3], off nt
	v_or_b32_e32 v2, s96, v25
	v_mad_u64_u32 v[2:3], s[88:89], v2, s54, 0
	v_add_u32_e32 v3, s6, v3
	v_lshl_add_u64 v[2:3], v[2:3], 2, v[6:7]
	global_load_dwordx4 v[80:83], v[2:3], off nt
	v_or_b32_e32 v2, s96, v26
	v_mad_u64_u32 v[2:3], s[88:89], v2, s54, 0
	v_add_u32_e32 v3, s6, v3
	v_lshl_add_u64 v[2:3], v[2:3], 2, v[6:7]
	global_load_dwordx4 v[84:87], v[2:3], off nt
	v_or_b32_e32 v2, s96, v27
	v_mad_u64_u32 v[2:3], s[88:89], v2, s54, 0
	v_add_u32_e32 v3, s6, v3
	v_lshl_add_u64 v[2:3], v[2:3], 2, v[6:7]
	global_load_dwordx4 v[88:91], v[2:3], off nt
	s_mul_i32 s6, s56, s93
	v_add_u32_e32 v2, s96, v28
	v_ashrrev_i32_e32 v5, 31, v2
	v_mad_u64_u32 v[2:3], s[88:89], v2, s54, 0
	v_mov_b32_e32 v4, v3
	v_mad_u64_u32 v[4:5], s[88:89], v5, s54, v[4:5]
	v_mov_b32_e32 v3, v4
	v_lshl_add_u64 v[2:3], v[2:3], 2, v[6:7]
	global_load_dwordx4 v[92:95], v[2:3], off nt
	s_lshl_b64 s[88:89], s[96:97], 1
	s_add_u32 s88, s94, s88
	s_addc_u32 s89, s95, s89
	s_waitcnt vmcnt(7)
	ds_write2_b32 v39, v64, v65 offset1:1
	ds_write2_b32 v39, v66, v67 offset0:2 offset1:3
	s_waitcnt vmcnt(6)
	ds_write2_b32 v40, v68, v69 offset1:1
	ds_write2_b32 v40, v70, v71 offset0:2 offset1:3
	s_waitcnt vmcnt(5)
	ds_write2_b32 v41, v72, v73 offset1:1
	ds_write2_b32 v41, v74, v75 offset0:2 offset1:3
	s_waitcnt vmcnt(4)
	ds_write2_b32 v42, v76, v77 offset1:1
	ds_write2_b32 v42, v78, v79 offset0:2 offset1:3
	s_waitcnt vmcnt(3)
	ds_write2_b32 v43, v80, v81 offset1:1
	ds_write2_b32 v44, v82, v83 offset1:1
	s_waitcnt vmcnt(2)
	ds_write2_b32 v45, v84, v85 offset1:1
	ds_write2_b32 v45, v86, v87 offset0:2 offset1:3
	s_waitcnt vmcnt(1)
	ds_write2_b32 v46, v88, v89 offset1:1
	ds_write2_b32 v47, v90, v91 offset1:1
	s_waitcnt vmcnt(0)
	ds_write2_b32 v48, v92, v93 offset1:1
	ds_write2_b32 v48, v94, v95 offset0:2 offset1:3
	s_waitcnt lgkmcnt(0)
	s_barrier
	ds_read_b32 v4, v29
	ds_read_b32 v5, v29 offset:1028
	v_lshl_add_u64 v[2:3], s[88:89], 0, v[16:17]
	s_waitcnt lgkmcnt(0)
	v_cvt_pk_bf16_f32 v4, v4, v5
	ds_read_b32 v5, v29 offset:2056
	ds_read_b32 v6, v29 offset:3084
	s_waitcnt lgkmcnt(0)
	v_cvt_pk_bf16_f32 v5, v5, v6
	ds_read_b32 v6, v29 offset:4112
	ds_read_b32 v7, v29 offset:5140
	s_waitcnt lgkmcnt(0)
	v_cvt_pk_bf16_f32 v6, v6, v7
	ds_read_b32 v7, v29 offset:6168
	ds_read_b32 v8, v29 offset:7196
	s_waitcnt lgkmcnt(0)
	v_cvt_pk_bf16_f32 v7, v7, v8
	v_or_b32_e32 v8, s92, v19
	v_mul_lo_u32 v10, s57, v8
	v_mad_u64_u32 v[8:9], s[88:89], s56, v8, 0
	v_add3_u32 v9, v9, s6, v10
	v_lshl_add_u64 v[8:9], v[8:9], 1, v[2:3]
	global_store_dwordx4 v[8:9], v[4:7], off
	ds_read_b32 v4, v31
	ds_read_b32 v5, v31 offset:1028
	s_waitcnt lgkmcnt(0)
	v_cvt_pk_bf16_f32 v4, v4, v5
	ds_read_b32 v5, v31 offset:2056
	ds_read_b32 v6, v31 offset:3084
	s_waitcnt lgkmcnt(0)
	v_cvt_pk_bf16_f32 v5, v5, v6
	ds_read_b32 v6, v31 offset:4112
	ds_read_b32 v7, v31 offset:5140
	s_waitcnt lgkmcnt(0)
	v_cvt_pk_bf16_f32 v6, v6, v7
	ds_read_b32 v7, v31 offset:6168
	ds_read_b32 v8, v31 offset:7196
	s_waitcnt lgkmcnt(0)
	v_cvt_pk_bf16_f32 v7, v7, v8
	v_or_b32_e32 v8, s92, v30
	v_mul_lo_u32 v10, s57, v8
	v_mad_u64_u32 v[8:9], s[88:89], s56, v8, 0
	v_add3_u32 v9, v9, s6, v10
	v_lshl_add_u64 v[8:9], v[8:9], 1, v[2:3]
	global_store_dwordx4 v[8:9], v[4:7], off
	ds_read_b32 v4, v33
	ds_read_b32 v5, v33 offset:1028
	s_waitcnt lgkmcnt(0)
	v_cvt_pk_bf16_f32 v4, v4, v5
	ds_read_b32 v5, v33 offset:2056
	ds_read_b32 v6, v33 offset:3084
	s_waitcnt lgkmcnt(0)
	v_cvt_pk_bf16_f32 v5, v5, v6
	ds_read_b32 v6, v33 offset:4112
	ds_read_b32 v7, v33 offset:5140
	s_waitcnt lgkmcnt(0)
	v_cvt_pk_bf16_f32 v6, v6, v7
	ds_read_b32 v7, v33 offset:6168
	ds_read_b32 v8, v33 offset:7196
	s_waitcnt lgkmcnt(0)
	v_cvt_pk_bf16_f32 v7, v7, v8
	v_or_b32_e32 v8, s92, v32
	v_mul_lo_u32 v10, s57, v8
	v_mad_u64_u32 v[8:9], s[88:89], s56, v8, 0
	v_add3_u32 v9, v9, s6, v10
	v_lshl_add_u64 v[8:9], v[8:9], 1, v[2:3]
	global_store_dwordx4 v[8:9], v[4:7], off
	ds_read_b32 v4, v35
	ds_read_b32 v5, v35 offset:1028
	s_waitcnt lgkmcnt(0)
	v_cvt_pk_bf16_f32 v4, v4, v5
	ds_read_b32 v5, v35 offset:2056
	ds_read_b32 v6, v35 offset:3084
	s_waitcnt lgkmcnt(0)
	v_cvt_pk_bf16_f32 v5, v5, v6
	ds_read_b32 v6, v35 offset:4112
	ds_read_b32 v7, v35 offset:5140
	s_waitcnt lgkmcnt(0)
	v_cvt_pk_bf16_f32 v6, v6, v7
	ds_read_b32 v7, v35 offset:6168
	ds_read_b32 v8, v35 offset:7196
	s_waitcnt lgkmcnt(0)
	v_cvt_pk_bf16_f32 v7, v7, v8
	v_add_u32_e32 v8, s92, v34
	v_ashrrev_i32_e32 v9, 31, v8
	v_mul_lo_u32 v10, s56, v9
	v_mul_lo_u32 v13, s57, v8
	v_mad_u64_u32 v[8:9], s[56:57], s56, v8, 0
	v_add3_u32 v9, v9, v10, v13
	v_lshl_add_u64 v[2:3], v[8:9], 1, v[2:3]
	global_store_dwordx4 v[2:3], v[4:7], off
	s_barrier

.LBB0_103:
	v_lshrrev_b32_e32 v2, 6, v1
	v_lshl_add_u32 v22, s2, 3, v2
	s_mov_b32 s0, 0x8200
	v_cmp_gt_i32_e32 vcc, s0, v22
	s_and_saveexec_b64 s[6:7], vcc
	s_cbranch_execz .LBB0_122
	v_lshlrev_b32_e32 v1, 2, v1
	v_and_b32_e32 v4, 0xfc, v1
	v_mbcnt_lo_u32_b32 v1, -1, 0
	v_mbcnt_hi_u32_b32 v3, -1, v1
	v_and_b32_e32 v1, 64, v3
	v_add_u32_e32 v5, 64, v1
	v_xor_b32_e32 v1, 32, v3
	v_cmp_lt_i32_e32 vcc, v1, v5
	v_xor_b32_e32 v6, 16, v3
	s_add_u32 s0, s86, 0x3b700000
	v_cndmask_b32_e32 v1, v3, v1, vcc
	v_cmp_lt_i32_e32 vcc, v6, v5
	v_mov_b32_e32 v25, 0
	v_lshlrev_b32_e32 v24, 2, v4
	v_cndmask_b32_e32 v6, v3, v6, vcc
	v_lshlrev_b32_e32 v48, 2, v6
	v_xor_b32_e32 v6, 8, v3
	v_cmp_lt_i32_e32 vcc, v6, v5
	s_addc_u32 s1, s87, 0
	s_lshl_b32 s3, s33, 3
	v_cndmask_b32_e32 v6, v3, v6, vcc
	v_lshlrev_b32_e32 v49, 2, v6
	v_xor_b32_e32 v6, 4, v3
	v_cmp_lt_i32_e32 vcc, v6, v5
	v_lshl_add_u64 v[26:27], s[52:53], 0, v[24:25]
	v_lshlrev_b32_e32 v24, 1, v4
	v_cndmask_b32_e32 v6, v3, v6, vcc
	v_lshlrev_b32_e32 v50, 2, v6
	v_xor_b32_e32 v6, 2, v3
	v_cmp_lt_i32_e32 vcc, v6, v5
	v_or_b32_e32 v8, 0x200, v4
	v_or_b32_e32 v10, 0x300, v4
	v_cndmask_b32_e32 v6, v3, v6, vcc
	v_lshlrev_b32_e32 v51, 2, v6
	v_xor_b32_e32 v6, 1, v3
	v_cmp_lt_i32_e32 vcc, v6, v5
	s_add_u32 s18, s84, 0x28600000
	v_lshl_add_u64 v[12:13], s[86:87], 0, v[24:25]
	v_cndmask_b32_e32 v3, v3, v6, vcc
	v_or_b32_e32 v6, 0x100, v4
	s_mov_b64 s[20:21], 0x30c00000
	v_lshlrev_b32_e32 v2, 5, v2
	v_lshlrev_b32_e32 v1, 2, v1
	v_lshlrev_b32_e32 v52, 2, v3
	s_addc_u32 s19, s85, 0
	v_lshl_add_u64 v[28:29], v[12:13], 0, s[20:21]
	v_lshl_add_u32 v53, s2, 8, v2
	s_lshl_b32 s30, s33, 8
	s_mov_b64 s[20:21], 0
	s_mov_b32 s31, 0x8000
	s_movk_i32 s34, 0x7fff
	v_lshlrev_b32_e32 v30, 2, v4
	v_mov_b32_e32 v31, v25
	s_mov_b64 s[22:23], 0x29208000
	s_movk_i32 s35, 0x3000
	v_mov_b64_e32 v[32:33], s[0:1]
	v_mov_b32_e32 v54, 0x358637bd
	s_mov_b32 s40, 0x800000
	s_movk_i32 s41, 0xfff
	s_mov_b64 s[24:25], 0x1000
	v_lshlrev_b32_e32 v34, 2, v6
	v_mov_b32_e32 v35, v25
	v_lshlrev_b32_e32 v36, 2, v8
	v_mov_b32_e32 v37, v25
	v_lshlrev_b32_e32 v38, 2, v10
	v_mov_b32_e32 v39, v25
	s_mov_b32 s44, 0x81ff
	global_load_dwordx4 v[106:109], v[26:27], off
	global_load_dwordx4 v[110:113], v[26:27], off offset:1024
	global_load_dwordx4 v[114:117], v[26:27], off offset:2048
	global_load_dwordx4 v[118:121], v[26:27], off offset:3072
	v_mov_b32_e32 v140, s8
	v_mov_b32_e32 v141, s9
	v_mov_b32_e32 v142, s10
	v_mov_b32_e32 v143, s11
	v_add_u32_e32 v138, 0xffff8000, v22
	v_cmp_lt_i32_e64 s[26:27], s34, v22
	v_mov_b32_e32 v139, 0
	s_nop 0
	v_cndmask_b32_e64 v138, v22, v138, s[26:27]
	v_cndmask_b32_e64 v144, v140, v142, s[26:27]
	v_cndmask_b32_e64 v145, v141, v143, s[26:27]
	v_lshlrev_b64 v[138:139], 12, v[138:139]
	v_lshl_add_u64 v[138:139], v[144:145], 0, v[138:139]
	v_lshl_add_u64 v[138:139], v[138:139], 0, v[30:31]
	global_load_dwordx4 v[134:137], v[138:139], off nt
	global_load_dwordx4 v[130:133], v[138:139], off offset:1024 nt
	global_load_dwordx4 v[126:129], v[138:139], off offset:2048 nt
	global_load_dwordx4 v[122:125], v[138:139], off offset:3072 nt
	s_waitcnt vmcnt(0)
	s_branch .LBB0_106

.LBB0_106:
	v_cmp_gt_i32_e32 vcc, s31, v22
	v_cmp_lt_i32_e64 s[0:1], s34, v22
	v_add_u32_e32 v24, 0xffff8000, v22
	v_ashrrev_i32_e32 v23, 31, v22
	s_waitcnt vmcnt(4)
	v_mov_b32_e32 v2, v122
	v_mov_b32_e32 v3, v123
	v_mov_b32_e32 v4, v124
	v_mov_b32_e32 v5, v125
	v_mov_b32_e32 v6, v126
	v_mov_b32_e32 v7, v127
	v_mov_b32_e32 v8, v128
	v_mov_b32_e32 v9, v129
	v_mov_b32_e32 v10, v130
	v_mov_b32_e32 v11, v131
	v_mov_b32_e32 v12, v132
	v_mov_b32_e32 v13, v133
	v_mov_b32_e32 v14, v134
	v_mov_b32_e32 v15, v135
	v_mov_b32_e32 v16, v136
	v_mov_b32_e32 v17, v137
	s_and_saveexec_b64 s[26:27], s[0:1]
	s_xor_b64 s[0:1], exec, s[26:27]
	v_and_b32_e32 v18, 0x7ffffc00, v53
	v_mov_b32_e32 v19, v25
	v_lshl_add_u64 v[18:19], v[18:19], 2, s[84:85]
	v_lshl_add_u64 v[46:47], v[18:19], 0, s[22:23]
	s_andn2_saveexec_b64 s[0:1], s[0:1]
	v_ashrrev_i32_e32 v18, 2, v22
	v_and_b32_e32 v18, 0xfffffc00, v18
	v_ashrrev_i32_e32 v19, 31, v18
	v_lshl_add_u64 v[46:47], v[18:19], 2, s[18:19]
	s_or_b64 exec, exec, s[0:1]
	v_lshrrev_b32_e32 v19, 5, v24
	v_ashrrev_i32_e32 v18, 12, v22
	v_add_u32_e32 v19, 8, v19
	v_cndmask_b32_e32 v18, v19, v18, vcc
	v_mad_i64_i32 v[18:19], s[0:1], v18, s35, v[32:33]
	v_lshl_add_u64 v[40:41], v[18:19], 0, s[24:25]
	v_lshl_add_u64 v[44:45], v[18:19], 0, v[30:31]
	v_lshl_add_u64 v[66:67], v[40:41], 0, v[30:31]
	v_lshl_add_u64 v[68:69], v[40:41], 0, v[34:35]
	v_lshl_add_u64 v[70:71], v[40:41], 0, v[36:37]
	v_lshl_add_u64 v[72:73], v[40:41], 0, v[38:39]
	global_load_dwordx4 v[74:77], v[66:67], off
	global_load_dwordx4 v[90:93], v[44:45], off
	global_load_dwordx4 v[78:81], v[68:69], off
	global_load_dwordx4 v[94:97], v[44:45], off offset:1024
	global_load_dwordx4 v[82:85], v[70:71], off
	global_load_dwordx4 v[98:101], v[44:45], off offset:2048
	global_load_dwordx4 v[86:89], v[72:73], off
	global_load_dwordx4 v[102:105], v[44:45], off offset:3072
	v_add_u32_e32 v146, s3, v22
	v_min_i32_e32 v146, s44, v146
	v_add_u32_e32 v138, 0xffff8000, v146
	v_cmp_lt_i32_e64 s[26:27], s34, v146
	v_mov_b32_e32 v139, 0
	s_nop 0
	v_cndmask_b32_e64 v138, v146, v138, s[26:27]
	v_cndmask_b32_e64 v144, v140, v142, s[26:27]
	v_cndmask_b32_e64 v145, v141, v143, s[26:27]
	v_lshlrev_b64 v[138:139], 12, v[138:139]
	v_lshl_add_u64 v[138:139], v[144:145], 0, v[138:139]
	v_lshl_add_u64 v[138:139], v[138:139], 0, v[30:31]
	global_load_dwordx4 v[134:137], v[138:139], off nt
	global_load_dwordx4 v[130:133], v[138:139], off offset:1024 nt
	global_load_dwordx4 v[126:129], v[138:139], off offset:2048 nt
	global_load_dwordx4 v[122:125], v[138:139], off offset:3072 nt
	v_mul_f32_e32 v18, v15, v15
	v_mul_f32_e32 v19, v11, v11
	v_mul_f32_e32 v20, v7, v7
	v_fmac_f32_e32 v18, v14, v14
	v_fmac_f32_e32 v19, v10, v10
	v_mul_f32_e32 v21, v3, v3
	v_fmac_f32_e32 v20, v6, v6
	v_fmac_f32_e32 v18, v16, v16
	v_fmac_f32_e32 v19, v12, v12
	v_fmac_f32_e32 v21, v2, v2
	v_fmac_f32_e32 v20, v8, v8
	v_fmac_f32_e32 v18, v17, v17
	v_fmac_f32_e32 v19, v13, v13
	v_fmac_f32_e32 v21, v4, v4
	v_fmac_f32_e32 v20, v9, v9
	v_add_f32_e32 v18, v18, v19
	v_add_f32_e32 v18, v18, v20
	v_fmac_f32_e32 v21, v5, v5
	v_add_f32_e32 v18, v18, v21
	ds_bpermute_b32 v19, v1, v18
	s_waitcnt lgkmcnt(0)
	v_add_f32_e32 v18, v18, v19
	ds_bpermute_b32 v19, v48, v18
	s_waitcnt lgkmcnt(0)
	v_add_f32_e32 v18, v18, v19
	ds_bpermute_b32 v19, v49, v18
	s_waitcnt lgkmcnt(0)
	v_add_f32_e32 v18, v18, v19
	ds_bpermute_b32 v19, v50, v18
	s_waitcnt lgkmcnt(0)
	v_add_f32_e32 v18, v18, v19
	ds_bpermute_b32 v19, v51, v18
	s_waitcnt lgkmcnt(0)
	v_add_f32_e32 v42, v18, v19
	ds_bpermute_b32 v43, v52, v42
	v_and_b32_e32 v55, 0xfff, v22
	s_waitcnt lgkmcnt(0)
	v_add_f32_e32 v24, v42, v43
	v_and_b32_e32 v64, 31, v22
	v_cmp_eq_u32_e64 s[0:1], s41, v55
	v_lshlrev_b64 v[42:43], 11, v[22:23]
	v_fmamk_f32 v23, v24, 0x3a800000, v54
	v_cndmask_b32_e64 v24, 0, 1, s[0:1]
	v_cmp_eq_u32_e64 s[0:1], 31, v64
	v_mul_f32_e32 v64, 0x4b800000, v23
	v_lshl_add_u64 v[42:43], v[28:29], 0, v[42:43]
	v_cndmask_b32_e64 v55, 0, 1, s[0:1]
	v_cmp_gt_f32_e64 s[0:1], s40, v23
	v_cndmask_b32_e32 v24, v55, v24, vcc
	v_and_b32_e32 v24, 1, v24
	v_cndmask_b32_e64 v23, v23, v64, s[0:1]
	v_rsq_f32_e32 v23, v23
	v_cmp_eq_u32_e32 vcc, 1, v24
	v_lshl_add_u64 v[46:47], v[46:47], 0, v[30:31]
	v_mul_f32_e32 v24, 0x45800000, v23
	v_cndmask_b32_e64 v23, v23, v24, s[0:1]
	s_waitcnt vmcnt(4)
	v_mul_f32_e32 v14, v14, v23
	v_mul_f32_e32 v15, v15, v23
	v_mul_f32_e32 v16, v16, v23
	v_mul_f32_e32 v17, v17, v23
	v_mul_f32_e32 v14, v14, v106
	v_mul_f32_e32 v15, v15, v107
	v_mul_f32_e32 v16, v16, v108
	v_mul_f32_e32 v17, v17, v109
	v_add_f32_e32 v56, 1.0, v74
	v_add_f32_e32 v57, 1.0, v75
	v_add_f32_e32 v58, 1.0, v76
	v_add_f32_e32 v59, 1.0, v77
	v_fma_f32 v90, v14, v56, v90
	v_fma_f32 v91, v15, v57, v91
	v_fma_f32 v92, v16, v58, v92
	v_fmac_f32_e32 v93, v17, v59
	v_cvt_pk_bf16_f32 v60, v90, v91
	v_cvt_pk_bf16_f32 v61, v92, v93
	global_store_dwordx2 v[42:43], v[60:61], off
	s_and_saveexec_b64 s[0:1], vcc
	s_cbranch_execz .Lnorm0_skip0
	global_store_dwordx4 v[46:47], v[90:93], off

.LBB0_531:
	v_cmp_gt_u32_e32 vcc, s30, v1
	s_waitcnt vmcnt(25)
	v_mov_b32_e32 v106, 0
	v_mov_b32_e32 v93, 0
	v_mov_b32_e32 v92, 0
	v_mov_b32_e32 v91, 0
	v_mov_b32_e32 v90, 0
	v_mov_b32_e32 v101, 0
	v_mov_b32_e32 v100, 0
	v_mov_b32_e32 v99, 0
	v_mov_b32_e32 v98, 0
	v_mov_b32_e32 v94, 0
	v_mov_b32_e32 v95, 0
	v_mov_b32_e32 v96, 0
	v_mov_b32_e32 v97, 0
	v_mov_b32_e32 v118, 0
	v_mov_b32_e32 v119, 0
	v_mov_b32_e32 v120, 0
	v_mov_b32_e32 v121, 0
	s_and_saveexec_b64 s[44:45], vcc
	s_cbranch_execz .LBB0_533
	v_add_u32_e32 v90, s56, v1
	v_ashrrev_i32_e32 v91, 31, v90
	v_lshlrev_b64 v[98:99], 12, v[90:91]
	v_lshl_or_b32 v98, v199, 1, v98
	v_lshl_add_u64 v[90:91], s[86:87], 0, v[98:99]
	v_lshl_add_u64 v[92:93], s[4:5], 0, v[98:99]
	v_lshl_add_u64 v[100:101], s[18:19], 0, v[98:99]
	global_load_dwordx4 v[94:97], v[90:91], off nt
	s_nop 0
	global_load_dwordx4 v[90:93], v[92:93], off nt
	v_lshl_add_u64 v[102:103], s[20:21], 0, v[98:99]
	global_load_dwordx4 v[98:101], v[100:101], off nt
	s_nop 0
	global_load_dwordx4 v[118:121], v[102:103], off nt

.LBB0_538:
	s_or_b64 exec, exec, s[44:45]
	s_add_i32 s58, s57, 1
	s_cmp_lt_u32 s58, s35
	s_cselect_b64 s[44:45], -1, 0
	s_cmp_ge_u32 s58, s35
	v_mov_b32_e32 v125, v121
	v_mov_b32_e32 v124, v120
	v_mov_b32_e32 v123, v119
	v_mov_b32_e32 v122, v118
	s_waitcnt lgkmcnt(0)
	s_barrier
	s_cbranch_scc1 .LBB0_544
	s_lshl_b32 s59, s58, 6
	v_add_u32_e32 v102, s59, v1
	v_cmp_gt_u32_e32 vcc, s30, v102
	v_mov_b32_e32 v105, 0
	v_mov_b32_e32 v93, 0
	v_mov_b32_e32 v92, 0
	v_mov_b32_e32 v91, 0
	v_mov_b32_e32 v90, 0
	v_mov_b32_e32 v101, 0
	v_mov_b32_e32 v100, 0
	v_mov_b32_e32 v99, 0
	v_mov_b32_e32 v98, 0
	v_mov_b32_e32 v94, 0
	v_mov_b32_e32 v95, 0
	v_mov_b32_e32 v96, 0
	v_mov_b32_e32 v97, 0
	v_mov_b32_e32 v122, 0
	v_mov_b32_e32 v123, 0
	v_mov_b32_e32 v124, 0
	v_mov_b32_e32 v125, 0
	s_and_saveexec_b64 s[50:51], vcc
	s_cbranch_execz .LBB0_541
	v_add_u32_e32 v90, s56, v102
	v_ashrrev_i32_e32 v91, 31, v90
	v_lshlrev_b64 v[98:99], 12, v[90:91]
	v_lshl_or_b32 v98, v199, 1, v98
	v_lshl_add_u64 v[90:91], s[86:87], 0, v[98:99]
	v_lshl_add_u64 v[92:93], s[4:5], 0, v[98:99]
	v_lshl_add_u64 v[100:101], s[18:19], 0, v[98:99]
	global_load_dwordx4 v[94:97], v[90:91], off nt
	s_nop 0
	global_load_dwordx4 v[90:93], v[92:93], off nt
	v_lshl_add_u64 v[102:103], s[20:21], 0, v[98:99]
	global_load_dwordx4 v[98:101], v[100:101], off nt
	s_nop 0
	global_load_dwordx4 v[122:125], v[102:103], off nt

.LBB0_612:
	s_min_i32 s6, s36, 60
	v_lshl_add_u32 v130, s37, 15, v145
	v_lshl_or_b32 v164, s38, 15, v146
	s_lshl_b32 s6, s6, 6
	v_readfirstlane_b32 s39, v130
	v_add_u32_e32 v166, 0x2000, v130
	v_add_u32_e32 v184, v164, v152
	v_add_u32_e32 v188, v164, v153
	v_lshl_add_u64 v[164:165], v[136:137], 0, s[6:7]
	s_waitcnt vmcnt(8)
	s_mov_b32 s51, s7
	v_add_u32_e32 v168, 0x4000, v130
	s_add_i32 s50, s6, 0xc0
	v_readfirstlane_b32 s52, v166
	v_lshl_add_u64 v[164:165], v[164:165], 0, s[24:25]
	s_mov_b32 m0, s39
	s_waitcnt lgkmcnt(0)
	s_barrier
	v_add_u32_e32 v130, 0x6000, v130
	v_lshl_add_u64 v[166:167], v[138:139], 0, s[6:7]
	v_readfirstlane_b32 s6, v168
	v_lshl_add_u64 v[168:169], v[140:141], 0, s[50:51]
	global_load_lds_dwordx4 v[164:165], off
	s_mov_b32 m0, s52
	v_readfirstlane_b32 s53, v130
	v_lshl_add_u64 v[166:167], v[166:167], 0, s[24:25]
	global_load_lds_dwordx4 v[168:169], off
	s_mov_b32 m0, s6
	v_lshl_add_u64 v[170:171], v[142:143], 0, s[50:51]
	global_load_lds_dwordx4 v[166:167], off
	s_mov_b32 m0, s53
	s_add_i32 s6, s38, 1
	global_load_lds_dwordx4 v[170:171], off
	ds_read_b128 v[164:167], v184 offset:16384
	ds_read_b128 v[168:171], v184 offset:17408
	ds_read_b128 v[172:175], v188
	ds_read_b128 v[176:179], v188 offset:1024
	ds_read_b128 v[180:183], v184 offset:18432
	ds_read_b128 v[184:187], v184 offset:19456
	s_waitcnt lgkmcnt(0)
	v_mfma_f32_16x16x32_bf16 v[126:129], v[164:167], v[172:175], v[126:129]
	s_cmp_lg_u32 s38, 3
	s_cselect_b32 s50, s6, 0
	s_add_i32 s6, s37, 1
	v_mfma_f32_16x16x32_bf16 v[122:125], v[168:171], v[172:175], v[122:125]
	s_cmp_lg_u32 s37, 3
	s_cselect_b32 s37, s6, 0
	s_add_i32 s6, s36, 1
	v_mfma_f32_16x16x32_bf16 v[118:121], v[180:183], v[172:175], v[118:121]
	s_min_i32 s6, s6, 60
	v_lshl_add_u32 v192, s37, 15, v145
	s_lshl_b32 s6, s6, 6
	v_mfma_f32_16x16x32_bf16 v[114:117], v[184:187], v[172:175], v[114:117]
	v_readfirstlane_b32 s51, v192
	v_add_u32_e32 v194, 0x2000, v192
	v_add_u32_e32 v195, 0x4000, v192
	v_mfma_f32_16x16x32_bf16 v[110:113], v[164:167], v[176:179], v[110:113]
	v_add_u32_e32 v197, 0x6000, v192
	v_lshl_add_u64 v[192:193], v[136:137], 0, s[6:7]
	s_mov_b32 s39, s7
	v_mfma_f32_16x16x32_bf16 v[106:109], v[168:171], v[176:179], v[106:109]
	s_add_i32 s38, s6, 0xc0
	v_readfirstlane_b32 s52, v194
	s_mov_b32 m0, s51
	v_mfma_f32_16x16x32_bf16 v[102:105], v[180:183], v[176:179], v[102:105]
	v_readfirstlane_b32 s53, v197
	v_lshl_or_b32 v130, s50, 15, v146
	v_add_u32_e32 v196, v130, v152
	v_mfma_f32_16x16x32_bf16 v[98:101], v[184:187], v[176:179], v[98:101]
	ds_read_b128 v[172:175], v188 offset:2048
	ds_read_b128 v[176:179], v188 offset:3072
	v_add_u32_e32 v130, v130, v153
	s_waitcnt lgkmcnt(0)
	v_mfma_f32_16x16x32_bf16 v[94:97], v[164:167], v[172:175], v[94:97]
	v_mfma_f32_16x16x32_bf16 v[90:93], v[168:171], v[172:175], v[90:93]
	v_mfma_f32_16x16x32_bf16 v[86:89], v[180:183], v[172:175], v[86:89]
	v_mfma_f32_16x16x32_bf16 v[82:85], v[184:187], v[172:175], v[82:85]
	v_mfma_f32_16x16x32_bf16 v[78:81], v[164:167], v[176:179], v[78:81]
	v_mfma_f32_16x16x32_bf16 v[74:77], v[168:171], v[176:179], v[74:77]
	v_mfma_f32_16x16x32_bf16 v[70:73], v[180:183], v[176:179], v[70:73]
	v_mfma_f32_16x16x32_bf16 v[66:69], v[184:187], v[176:179], v[66:69]
	ds_read_b128 v[172:175], v188 offset:4096
	ds_read_b128 v[176:179], v188 offset:5120
	s_waitcnt lgkmcnt(0)
	v_mfma_f32_16x16x32_bf16 v[62:65], v[164:167], v[172:175], v[62:65]
	v_mfma_f32_16x16x32_bf16 v[58:61], v[168:171], v[172:175], v[58:61]
	v_mfma_f32_16x16x32_bf16 v[54:57], v[180:183], v[172:175], v[54:57]
	v_mfma_f32_16x16x32_bf16 v[50:53], v[184:187], v[172:175], v[50:53]
	ds_read_b128 v[172:175], v188 offset:6144
	ds_read_b128 v[188:191], v188 offset:7168
	s_waitcnt vmcnt(8)
	s_waitcnt lgkmcnt(0)
	v_mfma_f32_16x16x32_bf16 v[46:49], v[164:167], v[176:179], v[46:49]
	s_barrier
	v_mfma_f32_16x16x32_bf16 v[42:45], v[168:171], v[176:179], v[42:45]
	v_mfma_f32_16x16x32_bf16 v[38:41], v[180:183], v[176:179], v[38:41]
	v_mfma_f32_16x16x32_bf16 v[34:37], v[184:187], v[176:179], v[34:37]
	v_lshl_add_u64 v[178:179], v[192:193], 0, s[24:25]
	v_lshl_add_u64 v[176:177], v[138:139], 0, s[6:7]
	v_readfirstlane_b32 s6, v195
	v_lshl_add_u64 v[192:193], v[140:141], 0, s[38:39]
	global_load_lds_dwordx4 v[178:179], off
	s_mov_b32 m0, s52
	v_lshl_add_u64 v[176:177], v[176:177], 0, s[24:25]
	global_load_lds_dwordx4 v[192:193], off
	s_mov_b32 m0, s6
	v_lshl_add_u64 v[194:195], v[142:143], 0, s[38:39]
	global_load_lds_dwordx4 v[176:177], off
	s_mov_b32 m0, s53
	s_waitcnt lgkmcnt(0)
	v_mfma_f32_16x16x32_bf16 v[30:33], v[164:167], v[172:175], v[30:33]
	global_load_lds_dwordx4 v[194:195], off
	s_add_i32 s6, s50, 1
	v_mfma_f32_16x16x32_bf16 v[26:29], v[168:171], v[172:175], v[26:29]
	s_cmp_lg_u32 s50, 3
	s_cselect_b32 s38, s6, 0
	s_add_i32 s6, s37, 1
	v_mfma_f32_16x16x32_bf16 v[22:25], v[180:183], v[172:175], v[22:25]
	s_cmp_lg_u32 s37, 3
	s_cselect_b32 s37, s6, 0
	s_add_i32 s36, s36, 2
	v_mfma_f32_16x16x32_bf16 v[18:21], v[184:187], v[172:175], v[18:21]
	s_cmp_lg_u32 s36, 64
	v_mfma_f32_16x16x32_bf16 v[14:17], v[164:167], v[188:191], v[14:17]
	v_mfma_f32_16x16x32_bf16 v[10:13], v[168:171], v[188:191], v[10:13]
	ds_read_b128 v[164:167], v196 offset:16384
	ds_read_b128 v[168:171], v196 offset:17408
	ds_read_b128 v[172:175], v130
	ds_read_b128 v[176:179], v130 offset:1024
	v_mfma_f32_16x16x32_bf16 v[6:9], v[180:183], v[188:191], v[6:9]
	ds_read_b128 v[180:183], v196 offset:18432
	v_mfma_f32_16x16x32_bf16 v[2:5], v[184:187], v[188:191], v[2:5]
	ds_read_b128 v[184:187], v196 offset:19456
	s_waitcnt lgkmcnt(0)
	v_mfma_f32_16x16x32_bf16 v[126:129], v[164:167], v[172:175], v[126:129]
	v_mfma_f32_16x16x32_bf16 v[122:125], v[168:171], v[172:175], v[122:125]
	v_mfma_f32_16x16x32_bf16 v[118:121], v[180:183], v[172:175], v[118:121]
	v_mfma_f32_16x16x32_bf16 v[114:117], v[184:187], v[172:175], v[114:117]
	v_mfma_f32_16x16x32_bf16 v[110:113], v[164:167], v[176:179], v[110:113]
	v_mfma_f32_16x16x32_bf16 v[106:109], v[168:171], v[176:179], v[106:109]
	v_mfma_f32_16x16x32_bf16 v[102:105], v[180:183], v[176:179], v[102:105]
	v_mfma_f32_16x16x32_bf16 v[98:101], v[184:187], v[176:179], v[98:101]
	ds_read_b128 v[172:175], v130 offset:2048
	ds_read_b128 v[176:179], v130 offset:3072
	s_waitcnt lgkmcnt(0)
	v_mfma_f32_16x16x32_bf16 v[94:97], v[164:167], v[172:175], v[94:97]
	v_mfma_f32_16x16x32_bf16 v[90:93], v[168:171], v[172:175], v[90:93]
	v_mfma_f32_16x16x32_bf16 v[86:89], v[180:183], v[172:175], v[86:89]
	v_mfma_f32_16x16x32_bf16 v[82:85], v[184:187], v[172:175], v[82:85]
	v_mfma_f32_16x16x32_bf16 v[78:81], v[164:167], v[176:179], v[78:81]
	v_mfma_f32_16x16x32_bf16 v[74:77], v[168:171], v[176:179], v[74:77]
	v_mfma_f32_16x16x32_bf16 v[70:73], v[180:183], v[176:179], v[70:73]
	v_mfma_f32_16x16x32_bf16 v[66:69], v[184:187], v[176:179], v[66:69]
	ds_read_b128 v[172:175], v130 offset:4096
	ds_read_b128 v[176:179], v130 offset:5120
	s_waitcnt lgkmcnt(0)
	v_mfma_f32_16x16x32_bf16 v[62:65], v[164:167], v[172:175], v[62:65]
	v_mfma_f32_16x16x32_bf16 v[58:61], v[168:171], v[172:175], v[58:61]
	v_mfma_f32_16x16x32_bf16 v[54:57], v[180:183], v[172:175], v[54:57]
	v_mfma_f32_16x16x32_bf16 v[50:53], v[184:187], v[172:175], v[50:53]
	v_mfma_f32_16x16x32_bf16 v[46:49], v[164:167], v[176:179], v[46:49]
	v_mfma_f32_16x16x32_bf16 v[42:45], v[168:171], v[176:179], v[42:45]
	v_mfma_f32_16x16x32_bf16 v[38:41], v[180:183], v[176:179], v[38:41]
	v_mfma_f32_16x16x32_bf16 v[34:37], v[184:187], v[176:179], v[34:37]
	ds_read_b128 v[172:175], v130 offset:6144
	ds_read_b128 v[176:179], v130 offset:7168
	s_waitcnt lgkmcnt(0)
	v_mfma_f32_16x16x32_bf16 v[30:33], v[164:167], v[172:175], v[30:33]
	v_mfma_f32_16x16x32_bf16 v[26:29], v[168:171], v[172:175], v[26:29]
	v_mfma_f32_16x16x32_bf16 v[22:25], v[180:183], v[172:175], v[22:25]
	v_mfma_f32_16x16x32_bf16 v[18:21], v[184:187], v[172:175], v[18:21]
	v_mfma_f32_16x16x32_bf16 v[14:17], v[164:167], v[176:179], v[14:17]
	v_mfma_f32_16x16x32_bf16 v[10:13], v[168:171], v[176:179], v[10:13]
	v_mfma_f32_16x16x32_bf16 v[6:9], v[180:183], v[176:179], v[6:9]
	v_mfma_f32_16x16x32_bf16 v[2:5], v[184:187], v[176:179], v[2:5]
	s_cbranch_scc1 .LBB0_612
	v_add_u32_e32 v130, s34, v151
	v_or_b32_e32 v138, v130, v1
	v_ashrrev_i32_e32 v142, 12, v130
	v_add_u32_e32 v130, 0xffff8000, v138
	v_lshrrev_b32_e32 v136, 5, v130
	v_add_u32_e32 v136, 8, v136
	v_cmp_gt_i32_e32 vcc, s40, v138
	v_or_b32_e32 v143, s35, v154
	s_waitcnt vmcnt(0)
	s_waitcnt lgkmcnt(0)
	s_barrier
	v_cndmask_b32_e32 v139, v136, v142, vcc
	v_mov_b64_e32 v[136:137], s[86:87]
	v_mad_i64_i32 v[140:141], s[34:35], v139, s41, v[136:137]
	v_mov_b32_e32 v139, v131
	v_lshlrev_b64 v[174:175], 12, v[138:139]
	v_ashrrev_i32_e32 v139, 31, v138
	v_lshl_add_u64 v[172:173], v[140:141], 0, s[26:27]
	v_lshlrev_b64 v[140:141], 12, v[130:131]
	v_lshlrev_b64 v[176:177], 12, v[138:139]
	v_lshl_add_u64 v[140:141], s[10:11], 0, v[140:141]
	v_lshl_add_u64 v[164:165], s[8:9], 0, v[176:177]
	v_lshlrev_b32_e32 v130, 2, v143
	v_cndmask_b32_e32 v141, v141, v165, vcc
	v_cndmask_b32_e32 v140, v140, v164, vcc
	v_lshl_add_u64 v[168:169], v[172:173], 0, v[130:131]
	v_lshl_add_u64 v[178:179], v[140:141], 0, v[130:131]
	v_cndmask_b32_e32 v175, v175, v177, vcc
	v_cndmask_b32_e32 v174, v174, v176, vcc
	v_lshl_add_u64 v[174:175], s[86:87], 0, v[174:175]
	v_mov_b32_e32 v141, v131
	v_or_b32_e32 v140, 64, v130
	v_lshl_add_u64 v[174:175], v[174:175], 0, v[130:131]
	v_lshl_add_u64 v[176:177], v[172:173], 0, v[140:141]
	global_load_dwordx4 v[184:187], v[178:179], off nt
	global_load_dwordx4 v[180:183], v[168:169], off
	global_load_dwordx4 v[188:191], v[176:177], off
	global_load_dwordx4 v[192:195], v[178:179], off offset:64 nt
	s_waitcnt vmcnt(2)
	v_fma_f32 v184, v126, v180, v184
	v_fma_f32 v185, v127, v181, v185
	v_fma_f32 v186, v128, v182, v186
	v_fmac_f32_e32 v187, v129, v183
	global_store_dwordx4 v[174:175], v[184:187], off
	v_mov_b32_e32 v127, v131
	v_or_b32_e32 v126, 0x80, v130
	v_lshl_add_u64 v[128:129], v[172:173], 0, v[126:127]
	global_load_dwordx4 v[180:183], v[128:129], off
	global_load_dwordx4 v[184:187], v[178:179], off offset:128 nt
	s_waitcnt vmcnt(3)
	v_fma_f32 v192, v122, v188, v192
	v_fma_f32 v193, v123, v189, v193
	v_fma_f32 v194, v124, v190, v194
	v_fmac_f32_e32 v195, v125, v191
	global_store_dwordx4 v[174:175], v[192:195], off offset:64
	v_mov_b32_e32 v123, v131
	v_or_b32_e32 v122, 0xc0, v130
	v_lshl_add_u64 v[124:125], v[172:173], 0, v[122:123]
	v_mov_b32_e32 v129, v131
	v_or_b32_e32 v128, 16, v138
	v_cmp_gt_i32_e32 vcc, s40, v128
	global_load_dwordx4 v[188:191], v[124:125], off
	global_load_dwordx4 v[192:195], v[178:179], off offset:192 nt
	s_waitcnt vmcnt(3)
	v_fma_f32 v184, v118, v180, v184
	v_fma_f32 v185, v119, v181, v185
	v_fma_f32 v186, v120, v182, v186
	v_fmac_f32_e32 v187, v121, v183
	global_store_dwordx4 v[174:175], v[184:187], off offset:128
	v_add_u32_e32 v124, 0xffff8010, v138
	v_lshrrev_b32_e32 v139, 5, v124
	v_mov_b32_e32 v125, v131
	v_lshlrev_b64 v[168:169], 12, v[128:129]
	v_ashrrev_i32_e32 v129, 31, v128
	v_add_u32_e32 v139, 8, v139
	v_lshlrev_b64 v[124:125], 12, v[124:125]
	v_lshlrev_b64 v[170:171], 12, v[128:129]
	v_cndmask_b32_e32 v139, v139, v142, vcc
	v_lshl_add_u64 v[124:125], s[10:11], 0, v[124:125]
	v_lshl_add_u64 v[128:129], s[8:9], 0, v[170:171]
	v_mad_i64_i32 v[172:173], s[34:35], v139, s41, v[136:137]
	v_cndmask_b32_e32 v125, v125, v129, vcc
	v_cndmask_b32_e32 v124, v124, v128, vcc
	v_lshl_add_u64 v[128:129], v[172:173], 0, s[26:27]
	v_lshl_add_u64 v[172:173], v[128:129], 0, v[130:131]
	v_lshl_add_u64 v[124:125], v[124:125], 0, v[130:131]
	global_load_dwordx4 v[180:183], v[172:173], off
	global_load_dwordx4 v[184:187], v[124:125], off nt
	s_waitcnt vmcnt(3)
	v_fma_f32 v192, v114, v188, v192
	v_fma_f32 v193, v115, v189, v193
	v_fma_f32 v194, v116, v190, v194
	v_fmac_f32_e32 v195, v117, v191
	global_store_dwordx4 v[174:175], v[192:195], off offset:192
	v_cndmask_b32_e32 v165, v169, v171, vcc
	v_cndmask_b32_e32 v164, v168, v170, vcc
	v_lshl_add_u64 v[164:165], s[86:87], 0, v[164:165]
	v_lshl_add_u64 v[164:165], v[164:165], 0, v[130:131]
	v_lshl_add_u64 v[166:167], v[128:129], 0, v[140:141]
	global_load_dwordx4 v[188:191], v[166:167], off
	global_load_dwordx4 v[192:195], v[124:125], off offset:64 nt
	s_waitcnt vmcnt(3)
	v_fma_f32 v184, v110, v180, v184
	v_fma_f32 v185, v111, v181, v185
	v_fma_f32 v186, v112, v182, v186
	v_fmac_f32_e32 v187, v113, v183
	global_store_dwordx4 v[164:165], v[184:187], off
	v_lshl_add_u64 v[118:119], v[128:129], 0, v[126:127]
	global_load_dwordx4 v[180:183], v[118:119], off
	global_load_dwordx4 v[184:187], v[124:125], off offset:128 nt
	s_waitcnt vmcnt(3)
	v_fma_f32 v192, v106, v188, v192
	v_fma_f32 v193, v107, v189, v193
	v_fma_f32 v194, v108, v190, v194
	v_fmac_f32_e32 v195, v109, v191
	global_store_dwordx4 v[164:165], v[192:195], off offset:64
	v_lshl_add_u64 v[114:115], v[128:129], 0, v[122:123]
	global_load_dwordx4 v[188:191], v[114:115], off
	global_load_dwordx4 v[192:195], v[124:125], off offset:192 nt
	s_waitcnt vmcnt(3)
	v_fma_f32 v184, v102, v180, v184
	v_fma_f32 v185, v103, v181, v185
	v_fma_f32 v186, v104, v182, v186
	v_fmac_f32_e32 v187, v105, v183
	global_store_dwordx4 v[164:165], v[184:187], off offset:128
	v_add_u32_e32 v110, 0xffff8020, v138
	v_mov_b32_e32 v113, v131
	v_or_b32_e32 v112, 32, v138
	v_lshrrev_b32_e32 v116, 5, v110
	v_mov_b32_e32 v111, v131
	v_lshlrev_b64 v[114:115], 12, v[112:113]
	v_ashrrev_i32_e32 v113, 31, v112
	v_add_u32_e32 v118, 8, v116
	v_cmp_gt_i32_e32 vcc, s40, v112
	v_lshlrev_b64 v[110:111], 12, v[110:111]
	v_lshlrev_b64 v[116:117], 12, v[112:113]
	v_cndmask_b32_e32 v118, v118, v142, vcc
	v_lshl_add_u64 v[110:111], s[10:11], 0, v[110:111]
	v_lshl_add_u64 v[112:113], s[8:9], 0, v[116:117]
	v_mad_i64_i32 v[118:119], s[34:35], v118, s41, v[136:137]
	v_cndmask_b32_e32 v111, v111, v113, vcc
	v_cndmask_b32_e32 v110, v110, v112, vcc
	v_lshl_add_u64 v[112:113], v[118:119], 0, s[26:27]
	v_lshl_add_u64 v[118:119], v[112:113], 0, v[130:131]
	v_lshl_add_u64 v[110:111], v[110:111], 0, v[130:131]
	global_load_dwordx4 v[180:183], v[118:119], off
	global_load_dwordx4 v[184:187], v[110:111], off nt
	s_waitcnt vmcnt(3)
	v_fma_f32 v192, v98, v188, v192
	v_fma_f32 v193, v99, v189, v193
	v_fma_f32 v194, v100, v190, v194
	v_fmac_f32_e32 v195, v101, v191
	global_store_dwordx4 v[164:165], v[192:195], off offset:192
	v_cndmask_b32_e32 v107, v115, v117, vcc
	v_cndmask_b32_e32 v106, v114, v116, vcc
	v_lshl_add_u64 v[106:107], s[86:87], 0, v[106:107]
	v_lshl_add_u64 v[106:107], v[106:107], 0, v[130:131]
	v_lshl_add_u64 v[108:109], v[112:113], 0, v[140:141]
	global_load_dwordx4 v[188:191], v[108:109], off
	global_load_dwordx4 v[192:195], v[110:111], off offset:64 nt
	s_waitcnt vmcnt(3)
	v_fma_f32 v184, v94, v180, v184
	v_fma_f32 v185, v95, v181, v185
	v_fma_f32 v186, v96, v182, v186
	v_fmac_f32_e32 v187, v97, v183
	global_store_dwordx4 v[106:107], v[184:187], off
	v_lshl_add_u64 v[102:103], v[112:113], 0, v[126:127]
	global_load_dwordx4 v[180:183], v[102:103], off
	global_load_dwordx4 v[184:187], v[110:111], off offset:128 nt
	s_waitcnt vmcnt(3)
	v_fma_f32 v192, v90, v188, v192
	v_fma_f32 v193, v91, v189, v193
	v_fma_f32 v194, v92, v190, v194
	v_fmac_f32_e32 v195, v93, v191
	global_store_dwordx4 v[106:107], v[192:195], off offset:64
	v_lshl_add_u64 v[98:99], v[112:113], 0, v[122:123]
	global_load_dwordx4 v[188:191], v[98:99], off
	global_load_dwordx4 v[192:195], v[110:111], off offset:192 nt
	s_waitcnt vmcnt(3)
	v_fma_f32 v184, v86, v180, v184
	v_fma_f32 v185, v87, v181, v185
	v_fma_f32 v186, v88, v182, v186
	v_fmac_f32_e32 v187, v89, v183
	global_store_dwordx4 v[106:107], v[184:187], off offset:128
	v_add_u32_e32 v94, 0xffff8030, v138
	v_mov_b32_e32 v97, v131
	v_or_b32_e32 v96, 48, v138
	v_lshrrev_b32_e32 v100, 5, v94
	v_mov_b32_e32 v95, v131
	v_lshlrev_b64 v[98:99], 12, v[96:97]
	v_ashrrev_i32_e32 v97, 31, v96
	v_add_u32_e32 v102, 8, v100
	v_cmp_gt_i32_e32 vcc, s40, v96
	v_lshlrev_b64 v[94:95], 12, v[94:95]
	v_lshlrev_b64 v[100:101], 12, v[96:97]
	v_cndmask_b32_e32 v102, v102, v142, vcc
	v_lshl_add_u64 v[94:95], s[10:11], 0, v[94:95]
	v_lshl_add_u64 v[96:97], s[8:9], 0, v[100:101]
	v_mad_i64_i32 v[102:103], s[34:35], v102, s41, v[136:137]
	v_cndmask_b32_e32 v95, v95, v97, vcc
	v_cndmask_b32_e32 v94, v94, v96, vcc
	v_lshl_add_u64 v[96:97], v[102:103], 0, s[26:27]
	v_lshl_add_u64 v[102:103], v[96:97], 0, v[130:131]
	v_lshl_add_u64 v[94:95], v[94:95], 0, v[130:131]
	global_load_dwordx4 v[180:183], v[102:103], off
	global_load_dwordx4 v[184:187], v[94:95], off nt
	s_waitcnt vmcnt(3)
	v_fma_f32 v192, v82, v188, v192
	v_fma_f32 v193, v83, v189, v193
	v_fma_f32 v194, v84, v190, v194
	v_fmac_f32_e32 v195, v85, v191
	global_store_dwordx4 v[106:107], v[192:195], off offset:192
	v_cndmask_b32_e32 v91, v99, v101, vcc
	v_cndmask_b32_e32 v90, v98, v100, vcc
	v_lshl_add_u64 v[90:91], s[86:87], 0, v[90:91]
	v_lshl_add_u64 v[90:91], v[90:91], 0, v[130:131]
	v_lshl_add_u64 v[92:93], v[96:97], 0, v[140:141]
	global_load_dwordx4 v[188:191], v[92:93], off
	global_load_dwordx4 v[192:195], v[94:95], off offset:64 nt
	s_waitcnt vmcnt(3)
	v_fma_f32 v184, v78, v180, v184
	v_fma_f32 v185, v79, v181, v185
	v_fma_f32 v186, v80, v182, v186
	v_fmac_f32_e32 v187, v81, v183
	global_store_dwordx4 v[90:91], v[184:187], off
	v_lshl_add_u64 v[86:87], v[96:97], 0, v[126:127]
	global_load_dwordx4 v[180:183], v[86:87], off
	global_load_dwordx4 v[184:187], v[94:95], off offset:128 nt
	s_waitcnt vmcnt(3)
	v_fma_f32 v192, v74, v188, v192
	v_fma_f32 v193, v75, v189, v193
	v_fma_f32 v194, v76, v190, v194
	v_fmac_f32_e32 v195, v77, v191
	global_store_dwordx4 v[90:91], v[192:195], off offset:64
	v_lshl_add_u64 v[82:83], v[96:97], 0, v[122:123]
	global_load_dwordx4 v[188:191], v[82:83], off
	global_load_dwordx4 v[192:195], v[94:95], off offset:192 nt
	s_waitcnt vmcnt(3)
	v_fma_f32 v184, v70, v180, v184
	v_fma_f32 v185, v71, v181, v185
	v_fma_f32 v186, v72, v182, v186
	v_fmac_f32_e32 v187, v73, v183
	global_store_dwordx4 v[90:91], v[184:187], off offset:128
	v_add_u32_e32 v78, 0xffff8040, v138
	v_mov_b32_e32 v81, v131
	v_or_b32_e32 v80, 64, v138
	v_lshrrev_b32_e32 v84, 5, v78
	v_mov_b32_e32 v79, v131
	v_lshlrev_b64 v[82:83], 12, v[80:81]
	v_ashrrev_i32_e32 v81, 31, v80
	v_add_u32_e32 v86, 8, v84
	v_cmp_gt_i32_e32 vcc, s40, v80
	v_lshlrev_b64 v[78:79], 12, v[78:79]
	v_lshlrev_b64 v[84:85], 12, v[80:81]
	v_cndmask_b32_e32 v86, v86, v142, vcc
	v_lshl_add_u64 v[78:79], s[10:11], 0, v[78:79]
	v_lshl_add_u64 v[80:81], s[8:9], 0, v[84:85]
	v_mad_i64_i32 v[86:87], s[34:35], v86, s41, v[136:137]
	v_cndmask_b32_e32 v79, v79, v81, vcc
	v_cndmask_b32_e32 v78, v78, v80, vcc
	v_lshl_add_u64 v[80:81], v[86:87], 0, s[26:27]
	v_lshl_add_u64 v[86:87], v[80:81], 0, v[130:131]
	v_lshl_add_u64 v[78:79], v[78:79], 0, v[130:131]
	global_load_dwordx4 v[180:183], v[86:87], off
	global_load_dwordx4 v[184:187], v[78:79], off nt
	s_waitcnt vmcnt(3)
	v_fma_f32 v192, v66, v188, v192
	v_fma_f32 v193, v67, v189, v193
	v_fma_f32 v194, v68, v190, v194
	v_fmac_f32_e32 v195, v69, v191
	global_store_dwordx4 v[90:91], v[192:195], off offset:192
	v_cndmask_b32_e32 v75, v83, v85, vcc
	v_cndmask_b32_e32 v74, v82, v84, vcc
	v_lshl_add_u64 v[74:75], s[86:87], 0, v[74:75]
	v_lshl_add_u64 v[74:75], v[74:75], 0, v[130:131]
	v_lshl_add_u64 v[76:77], v[80:81], 0, v[140:141]
	global_load_dwordx4 v[188:191], v[76:77], off
	global_load_dwordx4 v[192:195], v[78:79], off offset:64 nt
	s_waitcnt vmcnt(3)
	v_fma_f32 v184, v62, v180, v184
	v_fma_f32 v185, v63, v181, v185
	v_fma_f32 v186, v64, v182, v186
	v_fmac_f32_e32 v187, v65, v183
	global_store_dwordx4 v[74:75], v[184:187], off
	v_lshl_add_u64 v[70:71], v[80:81], 0, v[126:127]
	global_load_dwordx4 v[180:183], v[70:71], off
	global_load_dwordx4 v[184:187], v[78:79], off offset:128 nt
	s_waitcnt vmcnt(3)
	v_fma_f32 v192, v58, v188, v192
	v_fma_f32 v193, v59, v189, v193
	v_fma_f32 v194, v60, v190, v194
	v_fmac_f32_e32 v195, v61, v191
	global_store_dwordx4 v[74:75], v[192:195], off offset:64
	v_lshl_add_u64 v[66:67], v[80:81], 0, v[122:123]
	global_load_dwordx4 v[188:191], v[66:67], off
	global_load_dwordx4 v[192:195], v[78:79], off offset:192 nt
	s_waitcnt vmcnt(3)
	v_fma_f32 v184, v54, v180, v184
	v_fma_f32 v185, v55, v181, v185
	v_fma_f32 v186, v56, v182, v186
	v_fmac_f32_e32 v187, v57, v183
	global_store_dwordx4 v[74:75], v[184:187], off offset:128
	v_add_u32_e32 v62, 0xffff8050, v138
	v_mov_b32_e32 v65, v131
	v_or_b32_e32 v64, 0x50, v138
	v_lshrrev_b32_e32 v68, 5, v62
	v_mov_b32_e32 v63, v131
	v_lshlrev_b64 v[66:67], 12, v[64:65]
	v_ashrrev_i32_e32 v65, 31, v64
	v_add_u32_e32 v70, 8, v68
	v_cmp_gt_i32_e32 vcc, s40, v64
	v_lshlrev_b64 v[62:63], 12, v[62:63]
	v_lshlrev_b64 v[68:69], 12, v[64:65]
	v_cndmask_b32_e32 v70, v70, v142, vcc
	v_lshl_add_u64 v[62:63], s[10:11], 0, v[62:63]
	v_lshl_add_u64 v[64:65], s[8:9], 0, v[68:69]
	v_mad_i64_i32 v[70:71], s[34:35], v70, s41, v[136:137]
	v_cndmask_b32_e32 v63, v63, v65, vcc
	v_cndmask_b32_e32 v62, v62, v64, vcc
	v_lshl_add_u64 v[64:65], v[70:71], 0, s[26:27]
	v_lshl_add_u64 v[70:71], v[64:65], 0, v[130:131]
	v_lshl_add_u64 v[62:63], v[62:63], 0, v[130:131]
	global_load_dwordx4 v[180:183], v[70:71], off
	global_load_dwordx4 v[184:187], v[62:63], off nt
	s_waitcnt vmcnt(3)
	v_fma_f32 v192, v50, v188, v192
	v_fma_f32 v193, v51, v189, v193
	v_fma_f32 v194, v52, v190, v194
	v_fmac_f32_e32 v195, v53, v191
	global_store_dwordx4 v[74:75], v[192:195], off offset:192
	v_cndmask_b32_e32 v59, v67, v69, vcc
	v_cndmask_b32_e32 v58, v66, v68, vcc
	v_lshl_add_u64 v[58:59], s[86:87], 0, v[58:59]
	v_lshl_add_u64 v[58:59], v[58:59], 0, v[130:131]
	v_lshl_add_u64 v[60:61], v[64:65], 0, v[140:141]
	global_load_dwordx4 v[188:191], v[60:61], off
	global_load_dwordx4 v[192:195], v[62:63], off offset:64 nt
	s_waitcnt vmcnt(3)
	v_fma_f32 v184, v46, v180, v184
	v_fma_f32 v185, v47, v181, v185
	v_fma_f32 v186, v48, v182, v186
	v_fmac_f32_e32 v187, v49, v183
	global_store_dwordx4 v[58:59], v[184:187], off
	v_lshl_add_u64 v[54:55], v[64:65], 0, v[126:127]
	global_load_dwordx4 v[180:183], v[54:55], off
	global_load_dwordx4 v[184:187], v[62:63], off offset:128 nt
	s_waitcnt vmcnt(3)
	v_fma_f32 v192, v42, v188, v192
	v_fma_f32 v193, v43, v189, v193
	v_fma_f32 v194, v44, v190, v194
	v_fmac_f32_e32 v195, v45, v191
	global_store_dwordx4 v[58:59], v[192:195], off offset:64
	v_lshl_add_u64 v[50:51], v[64:65], 0, v[122:123]
	global_load_dwordx4 v[188:191], v[50:51], off
	global_load_dwordx4 v[192:195], v[62:63], off offset:192 nt
	s_waitcnt vmcnt(3)
	v_fma_f32 v184, v38, v180, v184
	v_fma_f32 v185, v39, v181, v185
	v_fma_f32 v186, v40, v182, v186
	v_fmac_f32_e32 v187, v41, v183
	global_store_dwordx4 v[58:59], v[184:187], off offset:128
	v_add_u32_e32 v46, 0xffff8060, v138
	v_mov_b32_e32 v49, v131
	v_or_b32_e32 v48, 0x60, v138
	v_lshrrev_b32_e32 v52, 5, v46
	v_mov_b32_e32 v47, v131
	v_lshlrev_b64 v[50:51], 12, v[48:49]
	v_ashrrev_i32_e32 v49, 31, v48
	v_add_u32_e32 v54, 8, v52
	v_cmp_gt_i32_e32 vcc, s40, v48
	v_lshlrev_b64 v[46:47], 12, v[46:47]
	v_lshlrev_b64 v[52:53], 12, v[48:49]
	v_cndmask_b32_e32 v54, v54, v142, vcc
	v_lshl_add_u64 v[46:47], s[10:11], 0, v[46:47]
	v_lshl_add_u64 v[48:49], s[8:9], 0, v[52:53]
	v_mad_i64_i32 v[54:55], s[34:35], v54, s41, v[136:137]
	v_cndmask_b32_e32 v47, v47, v49, vcc
	v_cndmask_b32_e32 v46, v46, v48, vcc
	v_lshl_add_u64 v[48:49], v[54:55], 0, s[26:27]
	v_lshl_add_u64 v[54:55], v[48:49], 0, v[130:131]
	v_lshl_add_u64 v[46:47], v[46:47], 0, v[130:131]
	global_load_dwordx4 v[180:183], v[54:55], off
	global_load_dwordx4 v[184:187], v[46:47], off nt
	s_waitcnt vmcnt(3)
	v_fma_f32 v192, v34, v188, v192
	v_fma_f32 v193, v35, v189, v193
	v_fma_f32 v194, v36, v190, v194
	v_fmac_f32_e32 v195, v37, v191
	global_store_dwordx4 v[58:59], v[192:195], off offset:192
	v_cndmask_b32_e32 v43, v51, v53, vcc
	v_cndmask_b32_e32 v42, v50, v52, vcc
	v_lshl_add_u64 v[42:43], s[86:87], 0, v[42:43]
	v_lshl_add_u64 v[42:43], v[42:43], 0, v[130:131]
	v_lshl_add_u64 v[44:45], v[48:49], 0, v[140:141]
	global_load_dwordx4 v[188:191], v[44:45], off
	global_load_dwordx4 v[192:195], v[46:47], off offset:64 nt
	s_waitcnt vmcnt(3)
	v_fma_f32 v184, v30, v180, v184
	v_fma_f32 v185, v31, v181, v185
	v_fma_f32 v186, v32, v182, v186
	v_fmac_f32_e32 v187, v33, v183
	global_store_dwordx4 v[42:43], v[184:187], off
	v_lshl_add_u64 v[38:39], v[48:49], 0, v[126:127]
	global_load_dwordx4 v[180:183], v[38:39], off
	global_load_dwordx4 v[184:187], v[46:47], off offset:128 nt
	s_waitcnt vmcnt(3)
	v_fma_f32 v192, v26, v188, v192
	v_fma_f32 v193, v27, v189, v193
	v_fma_f32 v194, v28, v190, v194
	v_fmac_f32_e32 v195, v29, v191
	global_store_dwordx4 v[42:43], v[192:195], off offset:64
	v_lshl_add_u64 v[34:35], v[48:49], 0, v[122:123]
	global_load_dwordx4 v[188:191], v[34:35], off
	global_load_dwordx4 v[192:195], v[46:47], off offset:192 nt
	s_waitcnt vmcnt(3)
	v_fma_f32 v184, v22, v180, v184
	v_fma_f32 v185, v23, v181, v185
	v_fma_f32 v186, v24, v182, v186
	v_fmac_f32_e32 v187, v25, v183
	global_store_dwordx4 v[42:43], v[184:187], off offset:128
	v_add_u32_e32 v30, 0xffff8070, v138
	v_mov_b32_e32 v33, v131
	v_or_b32_e32 v32, 0x70, v138
	v_lshrrev_b32_e32 v36, 5, v30
	v_mov_b32_e32 v31, v131
	v_lshlrev_b64 v[34:35], 12, v[32:33]
	v_ashrrev_i32_e32 v33, 31, v32
	v_add_u32_e32 v38, 8, v36
	v_cmp_gt_i32_e32 vcc, s40, v32
	v_lshlrev_b64 v[30:31], 12, v[30:31]
	v_lshlrev_b64 v[36:37], 12, v[32:33]
	v_cndmask_b32_e32 v38, v38, v142, vcc
	v_lshl_add_u64 v[30:31], s[10:11], 0, v[30:31]
	v_lshl_add_u64 v[32:33], s[8:9], 0, v[36:37]
	v_mad_i64_i32 v[38:39], s[34:35], v38, s41, v[136:137]
	v_cndmask_b32_e32 v31, v31, v33, vcc
	v_cndmask_b32_e32 v30, v30, v32, vcc
	v_lshl_add_u64 v[32:33], v[38:39], 0, s[26:27]
	v_lshl_add_u64 v[38:39], v[32:33], 0, v[130:131]
	v_lshl_add_u64 v[30:31], v[30:31], 0, v[130:131]
	global_load_dwordx4 v[180:183], v[38:39], off
	global_load_dwordx4 v[184:187], v[30:31], off nt
	s_waitcnt vmcnt(3)
	v_fma_f32 v192, v18, v188, v192
	v_fma_f32 v193, v19, v189, v193
	v_fma_f32 v194, v20, v190, v194
	v_fmac_f32_e32 v195, v21, v191
	global_store_dwordx4 v[42:43], v[192:195], off offset:192
	v_cndmask_b32_e32 v27, v35, v37, vcc
	v_cndmask_b32_e32 v26, v34, v36, vcc
	v_lshl_add_u64 v[26:27], s[86:87], 0, v[26:27]
	v_lshl_add_u64 v[26:27], v[26:27], 0, v[130:131]
	v_lshl_add_u64 v[28:29], v[32:33], 0, v[140:141]
	global_load_dwordx4 v[188:191], v[28:29], off
	global_load_dwordx4 v[192:195], v[30:31], off offset:64 nt
	s_waitcnt vmcnt(3)
	v_fma_f32 v184, v14, v180, v184
	v_fma_f32 v185, v15, v181, v185
	v_fma_f32 v186, v16, v182, v186
	v_fmac_f32_e32 v187, v17, v183
	global_store_dwordx4 v[26:27], v[184:187], off
	v_lshl_add_u64 v[22:23], v[32:33], 0, v[126:127]
	global_load_dwordx4 v[180:183], v[22:23], off
	global_load_dwordx4 v[184:187], v[30:31], off offset:128 nt
	s_waitcnt vmcnt(3)
	v_fma_f32 v192, v10, v188, v192
	v_fma_f32 v193, v11, v189, v193
	v_fma_f32 v194, v12, v190, v194
	v_fmac_f32_e32 v195, v13, v191
	global_store_dwordx4 v[26:27], v[192:195], off offset:64
	v_lshl_add_u64 v[18:19], v[32:33], 0, v[122:123]
	global_load_dwordx4 v[188:191], v[18:19], off
	global_load_dwordx4 v[192:195], v[30:31], off offset:192 nt
	s_waitcnt vmcnt(3)
	v_fma_f32 v184, v6, v180, v184
	v_fma_f32 v185, v7, v181, v185
	v_fma_f32 v186, v8, v182, v186
	v_fmac_f32_e32 v187, v9, v183
	global_store_dwordx4 v[26:27], v[184:187], off offset:128
	s_waitcnt vmcnt(1)
	v_fma_f32 v192, v2, v188, v192
	v_fma_f32 v193, v3, v189, v193
	v_fma_f32 v194, v4, v190, v194
	v_fmac_f32_e32 v195, v5, v191
	global_store_dwordx4 v[26:27], v[192:195], off offset:192
	s_barrier
	s_and_saveexec_b64 s[34:35], s[0:1]
	s_cbranch_execz .LBB0_606
	ds_write_b32 v155, v163
	s_branch .LBB0_606

.LBB0_1097:
	s_and_saveexec_b64 s[12:13], s[10:11]
	s_cbranch_execz .LBB0_983
	v_lshl_or_b32 v100, s75, 1, v100
	v_lshl_add_u64 v[4:5], v[92:93], 0, v[100:101]
	global_load_dwordx2 v[6:7], v[4:5], off nt
	global_load_dwordx2 v[8:9], v[4:5], off offset:32 nt
	global_load_dwordx2 v[10:11], v[4:5], off offset:64 nt
	global_load_dwordx2 v[12:13], v[4:5], off offset:96 nt
	global_load_dwordx2 v[14:15], v[4:5], off offset:128 nt
	global_load_dwordx2 v[16:17], v[4:5], off offset:160 nt
	global_load_dwordx2 v[18:19], v[4:5], off offset:192 nt
	global_load_dwordx2 v[20:21], v[4:5], off offset:224 nt
	v_lshl_add_u64 v[4:5], v[94:95], 0, v[100:101]
	s_waitcnt vmcnt(7)
	v_lshlrev_b32_e32 v2, 16, v6
	v_and_b32_e32 v6, 0xffff0000, v6
	v_lshlrev_b32_e32 v22, 16, v7
	v_and_b32_e32 v7, 0xffff0000, v7
	s_waitcnt vmcnt(6)
	v_lshlrev_b32_e32 v23, 16, v8
	v_and_b32_e32 v8, 0xffff0000, v8
	v_lshlrev_b32_e32 v24, 16, v9
	v_and_b32_e32 v9, 0xffff0000, v9
	s_waitcnt vmcnt(5)
	v_lshlrev_b32_e32 v25, 16, v10
	v_and_b32_e32 v10, 0xffff0000, v10
	v_lshlrev_b32_e32 v30, 16, v11
	v_and_b32_e32 v11, 0xffff0000, v11
	s_waitcnt vmcnt(4)
	v_lshlrev_b32_e32 v31, 16, v12
	v_and_b32_e32 v12, 0xffff0000, v12
	v_lshlrev_b32_e32 v32, 16, v13
	v_and_b32_e32 v13, 0xffff0000, v13
	s_waitcnt vmcnt(3)
	v_lshlrev_b32_e32 v33, 16, v14
	v_and_b32_e32 v14, 0xffff0000, v14
	v_lshlrev_b32_e32 v34, 16, v15
	v_and_b32_e32 v15, 0xffff0000, v15
	s_waitcnt vmcnt(2)
	v_lshlrev_b32_e32 v35, 16, v16
	v_and_b32_e32 v16, 0xffff0000, v16
	v_lshlrev_b32_e32 v36, 16, v17
	v_and_b32_e32 v17, 0xffff0000, v17
	v_mul_f32_e32 v2, v62, v2
	v_mul_f32_e32 v6, v63, v6
	v_mul_f32_e32 v22, v64, v22
	v_mul_f32_e32 v7, v65, v7
	v_mul_f32_e32 v23, v58, v23
	v_mul_f32_e32 v8, v59, v8
	v_mul_f32_e32 v24, v60, v24
	v_mul_f32_e32 v9, v61, v9
	v_mul_f32_e32 v25, v54, v25
	v_mul_f32_e32 v10, v55, v10
	v_mul_f32_e32 v30, v56, v30
	v_mul_f32_e32 v11, v57, v11
	v_mul_f32_e32 v31, v50, v31
	v_mul_f32_e32 v12, v51, v12
	v_mul_f32_e32 v32, v52, v32
	v_mul_f32_e32 v13, v53, v13
	v_mul_f32_e32 v33, v46, v33
	v_mul_f32_e32 v14, v47, v14
	v_mul_f32_e32 v34, v48, v34
	v_mul_f32_e32 v15, v49, v15
	v_mul_f32_e32 v35, v42, v35
	v_mul_f32_e32 v16, v43, v16
	v_mul_f32_e32 v36, v44, v36
	v_mul_f32_e32 v17, v45, v17
	v_cvt_pk_bf16_f32 v6, v2, v6
	v_cvt_pk_bf16_f32 v7, v22, v7
	v_cvt_pk_bf16_f32 v8, v23, v8
	v_cvt_pk_bf16_f32 v9, v24, v9
	v_cvt_pk_bf16_f32 v10, v25, v10
	v_cvt_pk_bf16_f32 v11, v30, v11
	v_cvt_pk_bf16_f32 v12, v31, v12
	v_cvt_pk_bf16_f32 v13, v32, v13
	v_cvt_pk_bf16_f32 v14, v33, v14
	v_cvt_pk_bf16_f32 v15, v34, v15
	v_cvt_pk_bf16_f32 v16, v35, v16
	v_cvt_pk_bf16_f32 v17, v36, v17
	global_store_dwordx2 v[4:5], v[6:7], off
	global_store_dwordx2 v[4:5], v[8:9], off offset:32
	global_store_dwordx2 v[4:5], v[10:11], off offset:64
	global_store_dwordx2 v[4:5], v[12:13], off offset:96
	global_store_dwordx2 v[4:5], v[14:15], off offset:128
	global_store_dwordx2 v[4:5], v[16:17], off offset:160
	s_waitcnt vmcnt(6)
	v_lshlrev_b32_e32 v2, 16, v20
	v_and_b32_e32 v6, 0xffff0000, v20
	v_mul_f32_e32 v2, v26, v2
	v_mul_f32_e32 v6, v27, v6
	v_lshlrev_b32_e32 v37, 16, v18
	v_and_b32_e32 v18, 0xffff0000, v18
	v_lshlrev_b32_e32 v66, 16, v19
	v_and_b32_e32 v19, 0xffff0000, v19
	v_cvt_pk_bf16_f32 v6, v2, v6
	v_lshlrev_b32_e32 v2, 16, v21
	v_and_b32_e32 v7, 0xffff0000, v21
	v_mul_f32_e32 v37, v38, v37
	v_mul_f32_e32 v18, v39, v18
	v_mul_f32_e32 v38, v40, v66
	v_mul_f32_e32 v19, v41, v19
	v_mul_f32_e32 v2, v28, v2
	v_mul_f32_e32 v7, v29, v7
	v_cvt_pk_bf16_f32 v18, v37, v18
	v_cvt_pk_bf16_f32 v19, v38, v19
	v_cvt_pk_bf16_f32 v7, v2, v7
	global_store_dwordx2 v[4:5], v[18:19], off offset:192
	global_store_dwordx2 v[4:5], v[6:7], off offset:224
	s_branch .LBB0_983

.LBB0_1154:
	s_min_i32 s4, s22, 60
	v_lshl_add_u32 v128, s23, 15, v144
	s_lshl_b32 s4, s4, 6
	v_readfirstlane_b32 s25, v128
	v_add_u32_e32 v166, 0x2000, v128
	v_lshl_add_u64 v[164:165], v[134:135], 0, s[4:5]
	s_waitcnt vmcnt(8)
	s_mov_b32 s35, s5
	v_add_u32_e32 v168, 0x4000, v128
	s_add_i32 s34, s4, 0xc0
	v_readfirstlane_b32 s31, v166
	v_lshl_add_u64 v[164:165], v[164:165], 0, s[14:15]
	s_mov_b32 m0, s25
	s_waitcnt lgkmcnt(0)
	s_barrier
	v_add_u32_e32 v128, 0x6000, v128
	v_lshl_add_u64 v[166:167], v[136:137], 0, s[4:5]
	v_readfirstlane_b32 s4, v168
	v_lshl_add_u64 v[168:169], v[138:139], 0, s[34:35]
	global_load_lds_dwordx4 v[164:165], off
	s_mov_b32 m0, s31
	v_readfirstlane_b32 s33, v128
	v_lshl_add_u64 v[166:167], v[166:167], 0, s[14:15]
	global_load_lds_dwordx4 v[168:169], off
	s_mov_b32 m0, s4
	v_lshl_or_b32 v163, s24, 15, v145
	v_lshl_add_u64 v[170:171], v[140:141], 0, s[34:35]
	global_load_lds_dwordx4 v[166:167], off
	s_mov_b32 m0, s33
	v_add_u32_e32 v184, v163, v151
	global_load_lds_dwordx4 v[170:171], off
	v_add_u32_e32 v163, v163, v152
	ds_read_b128 v[164:167], v184 offset:16384
	ds_read_b128 v[168:171], v184 offset:17408
	ds_read_b128 v[172:175], v163
	ds_read_b128 v[176:179], v163 offset:1024
	ds_read_b128 v[180:183], v184 offset:18432
	ds_read_b128 v[184:187], v184 offset:19456
	s_waitcnt lgkmcnt(0)
	v_mfma_f32_16x16x32_bf16 v[124:127], v[164:167], v[172:175], v[124:127]
	s_add_i32 s4, s24, 1
	s_cmp_lg_u32 s24, 3
	s_cselect_b32 s31, s4, 0
	v_mfma_f32_16x16x32_bf16 v[120:123], v[168:171], v[172:175], v[120:123]
	s_add_i32 s4, s23, 1
	s_cmp_lg_u32 s23, 3
	s_cselect_b32 s23, s4, 0
	v_mfma_f32_16x16x32_bf16 v[116:119], v[180:183], v[172:175], v[116:119]
	s_add_i32 s4, s22, 1
	s_min_i32 s4, s4, 60
	v_lshl_add_u32 v192, s23, 15, v144
	v_mfma_f32_16x16x32_bf16 v[112:115], v[184:187], v[172:175], v[112:115]
	s_lshl_b32 s4, s4, 6
	v_readfirstlane_b32 s33, v192
	v_add_u32_e32 v194, 0x4000, v192
	v_mfma_f32_16x16x32_bf16 v[108:111], v[164:167], v[176:179], v[108:111]
	v_add_u32_e32 v195, 0x6000, v192
	s_mov_b32 s25, s5
	s_add_i32 s24, s4, 0xc0
	v_mfma_f32_16x16x32_bf16 v[104:107], v[168:171], v[176:179], v[104:107]
	s_mov_b32 m0, s33
	v_readfirstlane_b32 s35, v195
	v_lshl_or_b32 v128, s31, 15, v145
	v_mfma_f32_16x16x32_bf16 v[100:103], v[180:183], v[176:179], v[100:103]
	v_add_u32_e32 v196, v128, v151
	v_add_u32_e32 v128, v128, v152
	v_mfma_f32_16x16x32_bf16 v[96:99], v[184:187], v[176:179], v[96:99]
	ds_read_b128 v[172:175], v163 offset:2048
	ds_read_b128 v[176:179], v163 offset:3072
	s_waitcnt lgkmcnt(0)
	v_mfma_f32_16x16x32_bf16 v[92:95], v[164:167], v[172:175], v[92:95]
	v_mfma_f32_16x16x32_bf16 v[88:91], v[168:171], v[172:175], v[88:91]
	v_mfma_f32_16x16x32_bf16 v[84:87], v[180:183], v[172:175], v[84:87]
	v_mfma_f32_16x16x32_bf16 v[80:83], v[184:187], v[172:175], v[80:83]
	v_mfma_f32_16x16x32_bf16 v[76:79], v[164:167], v[176:179], v[76:79]
	v_mfma_f32_16x16x32_bf16 v[72:75], v[168:171], v[176:179], v[72:75]
	v_mfma_f32_16x16x32_bf16 v[68:71], v[180:183], v[176:179], v[68:71]
	v_mfma_f32_16x16x32_bf16 v[64:67], v[184:187], v[176:179], v[64:67]
	ds_read_b128 v[172:175], v163 offset:4096
	ds_read_b128 v[176:179], v163 offset:5120
	s_waitcnt lgkmcnt(0)
	v_mfma_f32_16x16x32_bf16 v[60:63], v[164:167], v[172:175], v[60:63]
	v_mfma_f32_16x16x32_bf16 v[56:59], v[168:171], v[172:175], v[56:59]
	v_mfma_f32_16x16x32_bf16 v[52:55], v[180:183], v[172:175], v[52:55]
	v_mfma_f32_16x16x32_bf16 v[48:51], v[184:187], v[172:175], v[48:51]
	ds_read_b128 v[172:175], v163 offset:6144
	ds_read_b128 v[188:191], v163 offset:7168
	v_add_u32_e32 v163, 0x2000, v192
	v_lshl_add_u64 v[192:193], v[134:135], 0, s[4:5]
	v_mfma_f32_16x16x32_bf16 v[44:47], v[164:167], v[176:179], v[44:47]
	s_waitcnt vmcnt(8)
	v_readfirstlane_b32 s34, v163
	s_waitcnt lgkmcnt(0)
	v_mfma_f32_16x16x32_bf16 v[40:43], v[168:171], v[176:179], v[40:43]
	s_barrier
	v_mfma_f32_16x16x32_bf16 v[36:39], v[180:183], v[176:179], v[36:39]
	v_mfma_f32_16x16x32_bf16 v[32:35], v[184:187], v[176:179], v[32:35]
	v_lshl_add_u64 v[178:179], v[192:193], 0, s[14:15]
	v_lshl_add_u64 v[176:177], v[136:137], 0, s[4:5]
	v_readfirstlane_b32 s4, v194
	v_lshl_add_u64 v[192:193], v[138:139], 0, s[24:25]
	global_load_lds_dwordx4 v[178:179], off
	s_mov_b32 m0, s34
	v_lshl_add_u64 v[176:177], v[176:177], 0, s[14:15]
	global_load_lds_dwordx4 v[192:193], off
	s_mov_b32 m0, s4
	v_lshl_add_u64 v[194:195], v[140:141], 0, s[24:25]
	global_load_lds_dwordx4 v[176:177], off
	s_mov_b32 m0, s35
	s_waitcnt lgkmcnt(0)
	v_mfma_f32_16x16x32_bf16 v[28:31], v[164:167], v[172:175], v[28:31]
	global_load_lds_dwordx4 v[194:195], off
	s_add_i32 s4, s31, 1
	v_mfma_f32_16x16x32_bf16 v[24:27], v[168:171], v[172:175], v[24:27]
	s_cmp_lg_u32 s31, 3
	s_cselect_b32 s24, s4, 0
	s_add_i32 s4, s23, 1
	v_mfma_f32_16x16x32_bf16 v[20:23], v[180:183], v[172:175], v[20:23]
	s_cmp_lg_u32 s23, 3
	s_cselect_b32 s23, s4, 0
	s_add_i32 s22, s22, 2
	v_mfma_f32_16x16x32_bf16 v[16:19], v[184:187], v[172:175], v[16:19]
	s_cmp_lg_u32 s22, 64
	v_mfma_f32_16x16x32_bf16 v[12:15], v[164:167], v[188:191], v[12:15]
	v_mfma_f32_16x16x32_bf16 v[8:11], v[168:171], v[188:191], v[8:11]
	ds_read_b128 v[164:167], v196 offset:16384
	ds_read_b128 v[168:171], v196 offset:17408
	ds_read_b128 v[172:175], v128
	ds_read_b128 v[176:179], v128 offset:1024
	v_mfma_f32_16x16x32_bf16 v[4:7], v[180:183], v[188:191], v[4:7]
	ds_read_b128 v[180:183], v196 offset:18432
	v_mfma_f32_16x16x32_bf16 v[0:3], v[184:187], v[188:191], v[0:3]
	ds_read_b128 v[184:187], v196 offset:19456
	s_waitcnt lgkmcnt(0)
	v_mfma_f32_16x16x32_bf16 v[124:127], v[164:167], v[172:175], v[124:127]
	v_mfma_f32_16x16x32_bf16 v[120:123], v[168:171], v[172:175], v[120:123]
	v_mfma_f32_16x16x32_bf16 v[116:119], v[180:183], v[172:175], v[116:119]
	v_mfma_f32_16x16x32_bf16 v[112:115], v[184:187], v[172:175], v[112:115]
	v_mfma_f32_16x16x32_bf16 v[108:111], v[164:167], v[176:179], v[108:111]
	v_mfma_f32_16x16x32_bf16 v[104:107], v[168:171], v[176:179], v[104:107]
	v_mfma_f32_16x16x32_bf16 v[100:103], v[180:183], v[176:179], v[100:103]
	v_mfma_f32_16x16x32_bf16 v[96:99], v[184:187], v[176:179], v[96:99]
	ds_read_b128 v[172:175], v128 offset:2048
	ds_read_b128 v[176:179], v128 offset:3072
	s_waitcnt lgkmcnt(0)
	v_mfma_f32_16x16x32_bf16 v[92:95], v[164:167], v[172:175], v[92:95]
	v_mfma_f32_16x16x32_bf16 v[88:91], v[168:171], v[172:175], v[88:91]
	v_mfma_f32_16x16x32_bf16 v[84:87], v[180:183], v[172:175], v[84:87]
	v_mfma_f32_16x16x32_bf16 v[80:83], v[184:187], v[172:175], v[80:83]
	v_mfma_f32_16x16x32_bf16 v[76:79], v[164:167], v[176:179], v[76:79]
	v_mfma_f32_16x16x32_bf16 v[72:75], v[168:171], v[176:179], v[72:75]
	v_mfma_f32_16x16x32_bf16 v[68:71], v[180:183], v[176:179], v[68:71]
	v_mfma_f32_16x16x32_bf16 v[64:67], v[184:187], v[176:179], v[64:67]
	ds_read_b128 v[172:175], v128 offset:4096
	ds_read_b128 v[176:179], v128 offset:5120
	s_waitcnt lgkmcnt(0)
	v_mfma_f32_16x16x32_bf16 v[60:63], v[164:167], v[172:175], v[60:63]
	v_mfma_f32_16x16x32_bf16 v[56:59], v[168:171], v[172:175], v[56:59]
	v_mfma_f32_16x16x32_bf16 v[52:55], v[180:183], v[172:175], v[52:55]
	v_mfma_f32_16x16x32_bf16 v[48:51], v[184:187], v[172:175], v[48:51]
	v_mfma_f32_16x16x32_bf16 v[44:47], v[164:167], v[176:179], v[44:47]
	v_mfma_f32_16x16x32_bf16 v[40:43], v[168:171], v[176:179], v[40:43]
	v_mfma_f32_16x16x32_bf16 v[36:39], v[180:183], v[176:179], v[36:39]
	v_mfma_f32_16x16x32_bf16 v[32:35], v[184:187], v[176:179], v[32:35]
	ds_read_b128 v[172:175], v128 offset:6144
	ds_read_b128 v[176:179], v128 offset:7168
	s_waitcnt lgkmcnt(0)
	v_mfma_f32_16x16x32_bf16 v[28:31], v[164:167], v[172:175], v[28:31]
	v_mfma_f32_16x16x32_bf16 v[24:27], v[168:171], v[172:175], v[24:27]
	v_mfma_f32_16x16x32_bf16 v[20:23], v[180:183], v[172:175], v[20:23]
	v_mfma_f32_16x16x32_bf16 v[16:19], v[184:187], v[172:175], v[16:19]
	v_mfma_f32_16x16x32_bf16 v[12:15], v[164:167], v[176:179], v[12:15]
	v_mfma_f32_16x16x32_bf16 v[8:11], v[168:171], v[176:179], v[8:11]
	v_mfma_f32_16x16x32_bf16 v[4:7], v[180:183], v[176:179], v[4:7]
	v_mfma_f32_16x16x32_bf16 v[0:3], v[184:187], v[176:179], v[0:3]
	s_cbranch_scc1 .LBB0_1154
	v_add_u32_e32 v128, s20, v150
	v_or_b32_e32 v138, v128, v142
	v_ashrrev_i32_e32 v140, 12, v128
	v_add_u32_e32 v128, 0xffff8000, v138
	v_lshrrev_b32_e32 v134, 5, v128
	v_add_u32_e32 v134, 8, v134
	v_cmp_gt_i32_e32 vcc, s27, v138
	v_or_b32_e32 v141, s21, v153
	v_ashrrev_i32_e32 v139, 31, v138
	v_cndmask_b32_e32 v136, v134, v140, vcc
	v_mov_b64_e32 v[134:135], s[86:87]
	v_mad_i64_i32 v[136:137], s[20:21], v136, s28, v[134:135]
	v_lshl_add_u64 v[172:173], v[136:137], 0, s[16:17]
	v_lshlrev_b64 v[174:175], 12, v[138:139]
	v_lshlrev_b64 v[176:177], 12, v[128:129]
	v_lshlrev_b32_e32 v128, 2, v141
	s_waitcnt vmcnt(0)
	v_lshl_add_u64 v[136:137], s[86:87], 0, v[174:175]
	v_lshl_add_u64 v[164:165], v[172:173], 0, v[128:129]
	s_waitcnt lgkmcnt(0)
	s_barrier
	v_lshl_add_u64 v[178:179], v[136:137], 0, v[128:129]
	v_lshl_add_u64 v[174:175], s[84:85], 0, v[174:175]
	v_lshl_add_u64 v[176:177], s[2:3], 0, v[176:177]
	v_cndmask_b32_e32 v175, v177, v175, vcc
	v_cndmask_b32_e32 v174, v176, v174, vcc
	v_mov_b32_e32 v137, v129
	v_or_b32_e32 v136, 64, v128
	v_lshl_add_u64 v[174:175], v[174:175], 0, v[128:129]
	v_lshl_add_u64 v[176:177], v[172:173], 0, v[136:137]
	global_load_dwordx4 v[180:183], v[164:165], off
	global_load_dwordx4 v[184:187], v[178:179], off nt
	global_load_dwordx4 v[188:191], v[176:177], off
	global_load_dwordx4 v[192:195], v[178:179], off offset:64 nt
	s_waitcnt vmcnt(2)
	v_fma_f32 v184, v124, v180, v184
	v_fma_f32 v185, v125, v181, v185
	v_fma_f32 v186, v126, v182, v186
	v_fmac_f32_e32 v187, v127, v183
	global_store_dwordx4 v[174:175], v[184:187], off nt
	v_mov_b32_e32 v125, v129
	v_or_b32_e32 v124, 0x80, v128
	v_lshl_add_u64 v[126:127], v[172:173], 0, v[124:125]
	global_load_dwordx4 v[180:183], v[126:127], off
	global_load_dwordx4 v[184:187], v[178:179], off offset:128 nt
	s_waitcnt vmcnt(3)
	v_fma_f32 v192, v120, v188, v192
	v_fma_f32 v193, v121, v189, v193
	v_fma_f32 v194, v122, v190, v194
	v_fmac_f32_e32 v195, v123, v191
	global_store_dwordx4 v[174:175], v[192:195], off offset:64 nt
	v_mov_b32_e32 v121, v129
	v_or_b32_e32 v120, 0xc0, v128
	v_lshl_add_u64 v[122:123], v[172:173], 0, v[120:121]
	v_add_u32_e32 v126, 0xffff8010, v138
	v_lshrrev_b32_e32 v127, 5, v126
	v_add_u32_e32 v127, 8, v127
	global_load_dwordx4 v[188:191], v[122:123], off
	global_load_dwordx4 v[192:195], v[178:179], off offset:192 nt
	s_waitcnt vmcnt(3)
	v_fma_f32 v184, v116, v180, v184
	v_fma_f32 v185, v117, v181, v185
	v_fma_f32 v186, v118, v182, v186
	v_fmac_f32_e32 v187, v119, v183
	global_store_dwordx4 v[174:175], v[184:187], off offset:128 nt
	v_or_b32_e32 v122, 16, v138
	v_cmp_gt_i32_e32 vcc, s27, v122
	v_ashrrev_i32_e32 v123, 31, v122
	v_lshlrev_b64 v[168:169], 12, v[122:123]
	v_cndmask_b32_e32 v127, v127, v140, vcc
	v_mad_i64_i32 v[170:171], s[20:21], v127, s28, v[134:135]
	v_lshl_add_u64 v[170:171], v[170:171], 0, s[16:17]
	v_lshl_add_u64 v[122:123], s[86:87], 0, v[168:169]
	v_lshl_add_u64 v[172:173], v[170:171], 0, v[128:129]
	v_lshl_add_u64 v[122:123], v[122:123], 0, v[128:129]
	v_mov_b32_e32 v127, v129
	v_lshlrev_b64 v[126:127], 12, v[126:127]
	v_lshl_add_u64 v[126:127], s[2:3], 0, v[126:127]
	global_load_dwordx4 v[180:183], v[172:173], off
	global_load_dwordx4 v[184:187], v[122:123], off nt
	s_waitcnt vmcnt(3)
	v_fma_f32 v192, v112, v188, v192
	v_fma_f32 v193, v113, v189, v193
	v_fma_f32 v194, v114, v190, v194
	v_fmac_f32_e32 v195, v115, v191
	global_store_dwordx4 v[174:175], v[192:195], off offset:192 nt
	v_lshl_add_u64 v[164:165], s[84:85], 0, v[168:169]
	v_cndmask_b32_e32 v127, v127, v165, vcc
	v_cndmask_b32_e32 v126, v126, v164, vcc
	v_lshl_add_u64 v[126:127], v[126:127], 0, v[128:129]
	v_lshl_add_u64 v[164:165], v[170:171], 0, v[136:137]
	global_load_dwordx4 v[188:191], v[164:165], off
	global_load_dwordx4 v[192:195], v[122:123], off offset:64 nt
	s_waitcnt vmcnt(3)
	v_fma_f32 v184, v108, v180, v184
	v_fma_f32 v185, v109, v181, v185
	v_fma_f32 v186, v110, v182, v186
	v_fmac_f32_e32 v187, v111, v183
	global_store_dwordx4 v[126:127], v[184:187], off nt
	v_lshl_add_u64 v[116:117], v[170:171], 0, v[124:125]
	global_load_dwordx4 v[180:183], v[116:117], off
	global_load_dwordx4 v[184:187], v[122:123], off offset:128 nt
	s_waitcnt vmcnt(3)
	v_fma_f32 v192, v104, v188, v192
	v_fma_f32 v193, v105, v189, v193
	v_fma_f32 v194, v106, v190, v194
	v_fmac_f32_e32 v195, v107, v191
	global_store_dwordx4 v[126:127], v[192:195], off offset:64 nt
	v_lshl_add_u64 v[112:113], v[170:171], 0, v[120:121]
	global_load_dwordx4 v[188:191], v[112:113], off
	global_load_dwordx4 v[192:195], v[122:123], off offset:192 nt
	s_waitcnt vmcnt(3)
	v_fma_f32 v184, v100, v180, v184
	v_fma_f32 v185, v101, v181, v185
	v_fma_f32 v186, v102, v182, v186
	v_fmac_f32_e32 v187, v103, v183
	global_store_dwordx4 v[126:127], v[184:187], off offset:128 nt
	v_add_u32_e32 v110, 0xffff8020, v138
	v_or_b32_e32 v108, 32, v138
	v_lshrrev_b32_e32 v111, 5, v110
	v_add_u32_e32 v111, 8, v111
	v_cmp_gt_i32_e32 vcc, s27, v108
	v_ashrrev_i32_e32 v109, 31, v108
	v_lshlrev_b64 v[112:113], 12, v[108:109]
	v_cndmask_b32_e32 v111, v111, v140, vcc
	v_mad_i64_i32 v[114:115], s[20:21], v111, s28, v[134:135]
	v_lshl_add_u64 v[114:115], v[114:115], 0, s[16:17]
	v_lshl_add_u64 v[108:109], s[86:87], 0, v[112:113]
	v_lshl_add_u64 v[116:117], v[114:115], 0, v[128:129]
	v_lshl_add_u64 v[108:109], v[108:109], 0, v[128:129]
	v_mov_b32_e32 v111, v129
	global_load_dwordx4 v[180:183], v[116:117], off
	global_load_dwordx4 v[184:187], v[108:109], off nt
	s_waitcnt vmcnt(3)
	v_fma_f32 v192, v96, v188, v192
	v_fma_f32 v193, v97, v189, v193
	v_fma_f32 v194, v98, v190, v194
	v_fmac_f32_e32 v195, v99, v191
	global_store_dwordx4 v[126:127], v[192:195], off offset:192 nt
	v_lshlrev_b64 v[104:105], 12, v[110:111]
	v_lshl_add_u64 v[104:105], s[2:3], 0, v[104:105]
	v_lshl_add_u64 v[106:107], s[84:85], 0, v[112:113]
	v_cndmask_b32_e32 v105, v105, v107, vcc
	v_cndmask_b32_e32 v104, v104, v106, vcc
	v_lshl_add_u64 v[104:105], v[104:105], 0, v[128:129]
	v_lshl_add_u64 v[106:107], v[114:115], 0, v[136:137]
	global_load_dwordx4 v[188:191], v[106:107], off
	global_load_dwordx4 v[192:195], v[108:109], off offset:64 nt
	s_waitcnt vmcnt(3)
	v_fma_f32 v184, v92, v180, v184
	v_fma_f32 v185, v93, v181, v185
	v_fma_f32 v186, v94, v182, v186
	v_fmac_f32_e32 v187, v95, v183
	global_store_dwordx4 v[104:105], v[184:187], off nt
	v_lshl_add_u64 v[100:101], v[114:115], 0, v[124:125]
	global_load_dwordx4 v[180:183], v[100:101], off
	global_load_dwordx4 v[184:187], v[108:109], off offset:128 nt
	s_waitcnt vmcnt(3)
	v_fma_f32 v192, v88, v188, v192
	v_fma_f32 v193, v89, v189, v193
	v_fma_f32 v194, v90, v190, v194
	v_fmac_f32_e32 v195, v91, v191
	global_store_dwordx4 v[104:105], v[192:195], off offset:64 nt
	v_lshl_add_u64 v[96:97], v[114:115], 0, v[120:121]
	global_load_dwordx4 v[188:191], v[96:97], off
	global_load_dwordx4 v[192:195], v[108:109], off offset:192 nt
	s_waitcnt vmcnt(3)
	v_fma_f32 v184, v84, v180, v184
	v_fma_f32 v185, v85, v181, v185
	v_fma_f32 v186, v86, v182, v186
	v_fmac_f32_e32 v187, v87, v183
	global_store_dwordx4 v[104:105], v[184:187], off offset:128 nt
	v_add_u32_e32 v94, 0xffff8030, v138
	v_or_b32_e32 v92, 48, v138
	v_lshrrev_b32_e32 v95, 5, v94
	v_add_u32_e32 v95, 8, v95
	v_cmp_gt_i32_e32 vcc, s27, v92
	v_ashrrev_i32_e32 v93, 31, v92
	v_lshlrev_b64 v[96:97], 12, v[92:93]
	v_cndmask_b32_e32 v95, v95, v140, vcc
	v_mad_i64_i32 v[98:99], s[20:21], v95, s28, v[134:135]
	v_lshl_add_u64 v[98:99], v[98:99], 0, s[16:17]
	v_lshl_add_u64 v[92:93], s[86:87], 0, v[96:97]
	v_lshl_add_u64 v[100:101], v[98:99], 0, v[128:129]
	v_lshl_add_u64 v[92:93], v[92:93], 0, v[128:129]
	v_mov_b32_e32 v95, v129
	global_load_dwordx4 v[180:183], v[100:101], off
	global_load_dwordx4 v[184:187], v[92:93], off nt
	s_waitcnt vmcnt(3)
	v_fma_f32 v192, v80, v188, v192
	v_fma_f32 v193, v81, v189, v193
	v_fma_f32 v194, v82, v190, v194
	v_fmac_f32_e32 v195, v83, v191
	global_store_dwordx4 v[104:105], v[192:195], off offset:192 nt
	v_lshlrev_b64 v[88:89], 12, v[94:95]
	v_lshl_add_u64 v[88:89], s[2:3], 0, v[88:89]
	v_lshl_add_u64 v[90:91], s[84:85], 0, v[96:97]
	v_cndmask_b32_e32 v89, v89, v91, vcc
	v_cndmask_b32_e32 v88, v88, v90, vcc
	v_lshl_add_u64 v[88:89], v[88:89], 0, v[128:129]
	v_lshl_add_u64 v[90:91], v[98:99], 0, v[136:137]
	global_load_dwordx4 v[188:191], v[90:91], off
	global_load_dwordx4 v[192:195], v[92:93], off offset:64 nt
	s_waitcnt vmcnt(3)
	v_fma_f32 v184, v76, v180, v184
	v_fma_f32 v185, v77, v181, v185
	v_fma_f32 v186, v78, v182, v186
	v_fmac_f32_e32 v187, v79, v183
	global_store_dwordx4 v[88:89], v[184:187], off nt
	v_lshl_add_u64 v[84:85], v[98:99], 0, v[124:125]
	global_load_dwordx4 v[180:183], v[84:85], off
	global_load_dwordx4 v[184:187], v[92:93], off offset:128 nt
	s_waitcnt vmcnt(3)
	v_fma_f32 v192, v72, v188, v192
	v_fma_f32 v193, v73, v189, v193
	v_fma_f32 v194, v74, v190, v194
	v_fmac_f32_e32 v195, v75, v191
	global_store_dwordx4 v[88:89], v[192:195], off offset:64 nt
	v_lshl_add_u64 v[80:81], v[98:99], 0, v[120:121]
	global_load_dwordx4 v[188:191], v[80:81], off
	global_load_dwordx4 v[192:195], v[92:93], off offset:192 nt
	s_waitcnt vmcnt(3)
	v_fma_f32 v184, v68, v180, v184
	v_fma_f32 v185, v69, v181, v185
	v_fma_f32 v186, v70, v182, v186
	v_fmac_f32_e32 v187, v71, v183
	global_store_dwordx4 v[88:89], v[184:187], off offset:128 nt
	v_add_u32_e32 v78, 0xffff8040, v138
	v_or_b32_e32 v76, 64, v138
	v_lshrrev_b32_e32 v79, 5, v78
	v_add_u32_e32 v79, 8, v79
	v_cmp_gt_i32_e32 vcc, s27, v76
	v_ashrrev_i32_e32 v77, 31, v76
	v_lshlrev_b64 v[80:81], 12, v[76:77]
	v_cndmask_b32_e32 v79, v79, v140, vcc
	v_mad_i64_i32 v[82:83], s[20:21], v79, s28, v[134:135]
	v_lshl_add_u64 v[82:83], v[82:83], 0, s[16:17]
	v_lshl_add_u64 v[76:77], s[86:87], 0, v[80:81]
	v_lshl_add_u64 v[84:85], v[82:83], 0, v[128:129]
	v_lshl_add_u64 v[76:77], v[76:77], 0, v[128:129]
	v_mov_b32_e32 v79, v129
	global_load_dwordx4 v[180:183], v[84:85], off
	global_load_dwordx4 v[184:187], v[76:77], off nt
	s_waitcnt vmcnt(3)
	v_fma_f32 v192, v64, v188, v192
	v_fma_f32 v193, v65, v189, v193
	v_fma_f32 v194, v66, v190, v194
	v_fmac_f32_e32 v195, v67, v191
	global_store_dwordx4 v[88:89], v[192:195], off offset:192 nt
	v_lshlrev_b64 v[72:73], 12, v[78:79]
	v_lshl_add_u64 v[72:73], s[2:3], 0, v[72:73]
	v_lshl_add_u64 v[74:75], s[84:85], 0, v[80:81]
	v_cndmask_b32_e32 v73, v73, v75, vcc
	v_cndmask_b32_e32 v72, v72, v74, vcc
	v_lshl_add_u64 v[72:73], v[72:73], 0, v[128:129]
	v_lshl_add_u64 v[74:75], v[82:83], 0, v[136:137]
	global_load_dwordx4 v[188:191], v[74:75], off
	global_load_dwordx4 v[192:195], v[76:77], off offset:64 nt
	s_waitcnt vmcnt(3)
	v_fma_f32 v184, v60, v180, v184
	v_fma_f32 v185, v61, v181, v185
	v_fma_f32 v186, v62, v182, v186
	v_fmac_f32_e32 v187, v63, v183
	global_store_dwordx4 v[72:73], v[184:187], off nt
	v_lshl_add_u64 v[68:69], v[82:83], 0, v[124:125]
	global_load_dwordx4 v[180:183], v[68:69], off
	global_load_dwordx4 v[184:187], v[76:77], off offset:128 nt
	s_waitcnt vmcnt(3)
	v_fma_f32 v192, v56, v188, v192
	v_fma_f32 v193, v57, v189, v193
	v_fma_f32 v194, v58, v190, v194
	v_fmac_f32_e32 v195, v59, v191
	global_store_dwordx4 v[72:73], v[192:195], off offset:64 nt
	v_lshl_add_u64 v[64:65], v[82:83], 0, v[120:121]
	global_load_dwordx4 v[188:191], v[64:65], off
	global_load_dwordx4 v[192:195], v[76:77], off offset:192 nt
	s_waitcnt vmcnt(3)
	v_fma_f32 v184, v52, v180, v184
	v_fma_f32 v185, v53, v181, v185
	v_fma_f32 v186, v54, v182, v186
	v_fmac_f32_e32 v187, v55, v183
	global_store_dwordx4 v[72:73], v[184:187], off offset:128 nt
	v_add_u32_e32 v62, 0xffff8050, v138
	v_or_b32_e32 v60, 0x50, v138
	v_lshrrev_b32_e32 v63, 5, v62
	v_add_u32_e32 v63, 8, v63
	v_cmp_gt_i32_e32 vcc, s27, v60
	v_ashrrev_i32_e32 v61, 31, v60
	v_lshlrev_b64 v[64:65], 12, v[60:61]
	v_cndmask_b32_e32 v63, v63, v140, vcc
	v_mad_i64_i32 v[66:67], s[20:21], v63, s28, v[134:135]
	v_lshl_add_u64 v[66:67], v[66:67], 0, s[16:17]
	v_lshl_add_u64 v[60:61], s[86:87], 0, v[64:65]
	v_lshl_add_u64 v[68:69], v[66:67], 0, v[128:129]
	v_lshl_add_u64 v[60:61], v[60:61], 0, v[128:129]
	v_mov_b32_e32 v63, v129
	global_load_dwordx4 v[180:183], v[68:69], off
	global_load_dwordx4 v[184:187], v[60:61], off nt
	s_waitcnt vmcnt(3)
	v_fma_f32 v192, v48, v188, v192
	v_fma_f32 v193, v49, v189, v193
	v_fma_f32 v194, v50, v190, v194
	v_fmac_f32_e32 v195, v51, v191
	global_store_dwordx4 v[72:73], v[192:195], off offset:192 nt
	v_lshlrev_b64 v[56:57], 12, v[62:63]
	v_lshl_add_u64 v[56:57], s[2:3], 0, v[56:57]
	v_lshl_add_u64 v[58:59], s[84:85], 0, v[64:65]
	v_cndmask_b32_e32 v57, v57, v59, vcc
	v_cndmask_b32_e32 v56, v56, v58, vcc
	v_lshl_add_u64 v[56:57], v[56:57], 0, v[128:129]
	v_lshl_add_u64 v[58:59], v[66:67], 0, v[136:137]
	global_load_dwordx4 v[188:191], v[58:59], off
	global_load_dwordx4 v[192:195], v[60:61], off offset:64 nt
	s_waitcnt vmcnt(3)
	v_fma_f32 v184, v44, v180, v184
	v_fma_f32 v185, v45, v181, v185
	v_fma_f32 v186, v46, v182, v186
	v_fmac_f32_e32 v187, v47, v183
	global_store_dwordx4 v[56:57], v[184:187], off nt
	v_lshl_add_u64 v[52:53], v[66:67], 0, v[124:125]
	global_load_dwordx4 v[180:183], v[52:53], off
	global_load_dwordx4 v[184:187], v[60:61], off offset:128 nt
	s_waitcnt vmcnt(3)
	v_fma_f32 v192, v40, v188, v192
	v_fma_f32 v193, v41, v189, v193
	v_fma_f32 v194, v42, v190, v194
	v_fmac_f32_e32 v195, v43, v191
	global_store_dwordx4 v[56:57], v[192:195], off offset:64 nt
	v_lshl_add_u64 v[48:49], v[66:67], 0, v[120:121]
	global_load_dwordx4 v[188:191], v[48:49], off
	global_load_dwordx4 v[192:195], v[60:61], off offset:192 nt
	s_waitcnt vmcnt(3)
	v_fma_f32 v184, v36, v180, v184
	v_fma_f32 v185, v37, v181, v185
	v_fma_f32 v186, v38, v182, v186
	v_fmac_f32_e32 v187, v39, v183
	global_store_dwordx4 v[56:57], v[184:187], off offset:128 nt
	v_add_u32_e32 v46, 0xffff8060, v138
	v_or_b32_e32 v44, 0x60, v138
	v_lshrrev_b32_e32 v47, 5, v46
	v_add_u32_e32 v47, 8, v47
	v_cmp_gt_i32_e32 vcc, s27, v44
	v_ashrrev_i32_e32 v45, 31, v44
	v_lshlrev_b64 v[48:49], 12, v[44:45]
	v_cndmask_b32_e32 v47, v47, v140, vcc
	v_mad_i64_i32 v[50:51], s[20:21], v47, s28, v[134:135]
	v_lshl_add_u64 v[50:51], v[50:51], 0, s[16:17]
	v_lshl_add_u64 v[44:45], s[86:87], 0, v[48:49]
	v_lshl_add_u64 v[52:53], v[50:51], 0, v[128:129]
	v_lshl_add_u64 v[44:45], v[44:45], 0, v[128:129]
	v_mov_b32_e32 v47, v129
	global_load_dwordx4 v[180:183], v[52:53], off
	global_load_dwordx4 v[184:187], v[44:45], off nt
	s_waitcnt vmcnt(3)
	v_fma_f32 v192, v32, v188, v192
	v_fma_f32 v193, v33, v189, v193
	v_fma_f32 v194, v34, v190, v194
	v_fmac_f32_e32 v195, v35, v191
	global_store_dwordx4 v[56:57], v[192:195], off offset:192 nt
	v_lshlrev_b64 v[40:41], 12, v[46:47]
	v_lshl_add_u64 v[40:41], s[2:3], 0, v[40:41]
	v_lshl_add_u64 v[42:43], s[84:85], 0, v[48:49]
	v_cndmask_b32_e32 v41, v41, v43, vcc
	v_cndmask_b32_e32 v40, v40, v42, vcc
	v_lshl_add_u64 v[40:41], v[40:41], 0, v[128:129]
	v_lshl_add_u64 v[42:43], v[50:51], 0, v[136:137]
	global_load_dwordx4 v[188:191], v[42:43], off
	global_load_dwordx4 v[192:195], v[44:45], off offset:64 nt
	s_waitcnt vmcnt(3)
	v_fma_f32 v184, v28, v180, v184
	v_fma_f32 v185, v29, v181, v185
	v_fma_f32 v186, v30, v182, v186
	v_fmac_f32_e32 v187, v31, v183
	global_store_dwordx4 v[40:41], v[184:187], off nt
	v_lshl_add_u64 v[36:37], v[50:51], 0, v[124:125]
	global_load_dwordx4 v[180:183], v[36:37], off
	global_load_dwordx4 v[184:187], v[44:45], off offset:128 nt
	s_waitcnt vmcnt(3)
	v_fma_f32 v192, v24, v188, v192
	v_fma_f32 v193, v25, v189, v193
	v_fma_f32 v194, v26, v190, v194
	v_fmac_f32_e32 v195, v27, v191
	global_store_dwordx4 v[40:41], v[192:195], off offset:64 nt
	v_lshl_add_u64 v[32:33], v[50:51], 0, v[120:121]
	global_load_dwordx4 v[188:191], v[32:33], off
	global_load_dwordx4 v[192:195], v[44:45], off offset:192 nt
	s_waitcnt vmcnt(3)
	v_fma_f32 v184, v20, v180, v184
	v_fma_f32 v185, v21, v181, v185
	v_fma_f32 v186, v22, v182, v186
	v_fmac_f32_e32 v187, v23, v183
	global_store_dwordx4 v[40:41], v[184:187], off offset:128 nt
	v_add_u32_e32 v30, 0xffff8070, v138
	v_or_b32_e32 v28, 0x70, v138
	v_lshrrev_b32_e32 v31, 5, v30
	v_add_u32_e32 v31, 8, v31
	v_cmp_gt_i32_e32 vcc, s27, v28
	v_ashrrev_i32_e32 v29, 31, v28
	v_lshlrev_b64 v[32:33], 12, v[28:29]
	v_cndmask_b32_e32 v31, v31, v140, vcc
	v_mad_i64_i32 v[34:35], s[20:21], v31, s28, v[134:135]
	v_lshl_add_u64 v[34:35], v[34:35], 0, s[16:17]
	v_lshl_add_u64 v[28:29], s[86:87], 0, v[32:33]
	v_lshl_add_u64 v[36:37], v[34:35], 0, v[128:129]
	v_lshl_add_u64 v[28:29], v[28:29], 0, v[128:129]
	v_mov_b32_e32 v31, v129
	global_load_dwordx4 v[180:183], v[36:37], off
	global_load_dwordx4 v[184:187], v[28:29], off nt
	s_waitcnt vmcnt(3)
	v_fma_f32 v192, v16, v188, v192
	v_fma_f32 v193, v17, v189, v193
	v_fma_f32 v194, v18, v190, v194
	v_fmac_f32_e32 v195, v19, v191
	global_store_dwordx4 v[40:41], v[192:195], off offset:192 nt
	v_lshlrev_b64 v[24:25], 12, v[30:31]
	v_lshl_add_u64 v[24:25], s[2:3], 0, v[24:25]
	v_lshl_add_u64 v[26:27], s[84:85], 0, v[32:33]
	v_cndmask_b32_e32 v25, v25, v27, vcc
	v_cndmask_b32_e32 v24, v24, v26, vcc
	v_lshl_add_u64 v[24:25], v[24:25], 0, v[128:129]
	v_lshl_add_u64 v[26:27], v[34:35], 0, v[136:137]
	global_load_dwordx4 v[188:191], v[26:27], off
	global_load_dwordx4 v[192:195], v[28:29], off offset:64 nt
	s_waitcnt vmcnt(3)
	v_fma_f32 v184, v12, v180, v184
	v_fma_f32 v185, v13, v181, v185
	v_fma_f32 v186, v14, v182, v186
	v_fmac_f32_e32 v187, v15, v183
	global_store_dwordx4 v[24:25], v[184:187], off nt
	v_lshl_add_u64 v[20:21], v[34:35], 0, v[124:125]
	global_load_dwordx4 v[180:183], v[20:21], off
	global_load_dwordx4 v[184:187], v[28:29], off offset:128 nt
	s_waitcnt vmcnt(3)
	v_fma_f32 v192, v8, v188, v192
	v_fma_f32 v193, v9, v189, v193
	v_fma_f32 v194, v10, v190, v194
	v_fmac_f32_e32 v195, v11, v191
	global_store_dwordx4 v[24:25], v[192:195], off offset:64 nt
	v_lshl_add_u64 v[16:17], v[34:35], 0, v[120:121]
	global_load_dwordx4 v[188:191], v[16:17], off
	global_load_dwordx4 v[192:195], v[28:29], off offset:192 nt
	s_waitcnt vmcnt(3)
	v_fma_f32 v184, v4, v180, v184
	v_fma_f32 v185, v5, v181, v185
	v_fma_f32 v186, v6, v182, v186
	v_fmac_f32_e32 v187, v7, v183
	global_store_dwordx4 v[24:25], v[184:187], off offset:128 nt
	s_waitcnt vmcnt(1)
	v_fma_f32 v192, v0, v188, v192
	v_fma_f32 v193, v1, v189, v193
	v_fma_f32 v194, v2, v190, v194
	v_fmac_f32_e32 v195, v3, v191
	global_store_dwordx4 v[24:25], v[192:195], off offset:192 nt
	s_barrier
	s_and_saveexec_b64 s[20:21], s[0:1]
	s_cbranch_execz .LBB0_1148
	ds_write_b32 v154, v162
	s_branch .LBB0_1148
